# in-projection GEMM epilogue rewritten by hand: scalar class dispatch per 16-column group (SiLU only on gate columns, scaling only on q columns), SGPR base + 32-bit lane offsets instead of per-element
# speedup vs baseline: 1.0862x; 1.0044x over previous
; DI u16 f2bf(float x) { unsigned u = __float_as_uint(x); u += 0x7fffu + ((u >> 16) & 1u); return (u16)(u >> 16); }
; DI void phase_inproj(const Params& p, int layer, char* lds) {
;     ...
;     const int wr8 = w >> 2, wc8 = w & 3, fr = lane & 15, fq = lane >> 4;
; #pragma unroll
;     for (int bj = 0; bj < 2; ++bj)
; #pragma unroll
;       for (int n = 0; n < 2; ++n) {
;         const int cw = n0 + bj * 128 + wc8 * 32 + n * 16, col = cw + fr;
;         u16* dst = H + cw; int dstr = DIN;
;         {
;           const int bb = m0 / S;
;           if (cw >= C_DK && cw < C_DV) { const int o = cw - C_DK; dst = (u16*)(p.ws + OFF_DK) + ((size_t)(bb * 3 * S + (o >> 6) * S) << 6) + (o & 63); dstr = 64; }
;           else if (cw >= C_DV && cw < C_SQ) { const int o = cw - C_DV; dst = (u16*)(p.ws + OFF_DV) + ((size_t)(bb * 3 * S + (o >> 6) * S) << 6) + (o & 63); dstr = 64; }
;           else if (cw >= C_SK && cw < C_SV) { const int o = cw - C_SK; dst = (u16*)(p.ws + OFF_SK) + ((size_t)(bb * 1 * S + (o >> 6) * S) << 6) + (o & 63); dstr = 64; }
;           else if (cw >= C_SV && cw < C_GATE) { const int o = cw - C_SV; dst = (u16*)(p.ws + OFF_SV) + ((size_t)(bb * 1 * S + (o >> 6) * S) << 6) + (o & 63); dstr = 64; }
;         }
;         if (cw < DIN) {
;           float sc = 1.f;
;           if (col >= C_DQ && col < C_DK) sc = SC_DQ;
;           if (col >= C_SQ && col < C_SK) sc = SC_SQ;
;           const bool gate = col >= C_GATE;
; #pragma unroll
;           for (int ai = 0; ai < 2; ++ai)
; #pragma unroll
;             for (int m = 0; m < 4; ++m) {
; #pragma unroll
;               for (int j = 0; j < 4; ++j) {
;                 const int row = m0 + ai * 128 + wr8 * 64 + m * 16 + fq * 4 + j;
;                 float v = acc[ai][bj][m][n][j] * sc;
;                 if (gate) v = v * __builtin_amdgcn_rcpf(1.f + __expf(-v));
;                 dst[(size_t)row * dstr + fr] = f2bf(v);
;               }
;               __builtin_amdgcn_sched_barrier(0);
;             }
;         }
.LBB0_88:
	s_or_b64 exec, exec, s[8:9]
	s_nop 7
	v_mov_b32_e32 v137, 0x15c0
	v_mul_u32_u24_e32 v132, v144, v137
	v_lshl_add_u32 v132, v130, 1, v132
	v_add_u32_e32 v133, 0x15c0, v132
	v_add_u32_e32 v134, 0x2b80, v132
	v_add_u32_e32 v135, 0x4140, v132
	v_lshlrev_b32_e32 v136, 7, v144
	v_lshl_add_u32 v136, v130, 1, v136
	v_readfirstlane_b32 s26, v131
	s_lshr_b32 s27, s4, 13
	s_add_u32 s25, s6, s26
	s_cmpk_ge_u32 s25, 2784
	s_cbranch_scc1 .Lipe0_done
	s_cmpk_ge_u32 s25, 1760
	s_cbranch_scc1 .Lipe0_gate
	s_cmpk_ge_u32 s25, 1632
	s_cbranch_scc1 .Lipe0_sv
	s_cmpk_ge_u32 s25, 1504
	s_cbranch_scc1 .Lipe0_sk
	s_cmpk_ge_u32 s25, 1120
	s_cbranch_scc1 .Lipe0_sq
	s_cmpk_ge_u32 s25, 864
	s_cbranch_scc1 .Lipe0_dv
	s_cmpk_ge_u32 s25, 608
	s_cbranch_scc1 .Lipe0_dk
	s_cmpk_ge_u32 s25, 352
	s_cbranch_scc1 .Lipe0_dq
	s_mul_i32 s10, s4, 0x15c0
	s_lshl_b32 s11, s25, 1
	s_add_u32 s10, s10, s11
	s_add_u32 s8, s50, s10
	s_addc_u32 s9, s51, 0
	v_cvt_pk_bf16_f32 v137, v126, v127
	global_store_short v132, v137, s[8:9]
	global_store_short_d16_hi v133, v137, s[8:9]
	v_cvt_pk_bf16_f32 v138, v128, v129
	global_store_short v134, v138, s[8:9]
	global_store_short_d16_hi v135, v138, s[8:9]
	v_cvt_pk_bf16_f32 v137, v122, v123
	v_add_u32_e32 v139, 0x15c00, v132
	v_add_u32_e32 v140, 0x15c00, v133
	global_store_short v139, v137, s[8:9]
	global_store_short_d16_hi v140, v137, s[8:9]
	v_cvt_pk_bf16_f32 v138, v124, v125
	v_add_u32_e32 v139, 0x15c00, v134
	v_add_u32_e32 v140, 0x15c00, v135
	global_store_short v139, v138, s[8:9]
	global_store_short_d16_hi v140, v138, s[8:9]
	v_cvt_pk_bf16_f32 v137, v118, v119
	v_add_u32_e32 v139, 0x2b800, v132
	v_add_u32_e32 v140, 0x2b800, v133
	global_store_short v139, v137, s[8:9]
	global_store_short_d16_hi v140, v137, s[8:9]
	v_cvt_pk_bf16_f32 v138, v120, v121
	v_add_u32_e32 v139, 0x2b800, v134
	v_add_u32_e32 v140, 0x2b800, v135
	global_store_short v139, v138, s[8:9]
	global_store_short_d16_hi v140, v138, s[8:9]
	v_cvt_pk_bf16_f32 v137, v114, v115
	v_add_u32_e32 v139, 0x41400, v132
	v_add_u32_e32 v140, 0x41400, v133
	global_store_short v139, v137, s[8:9]
	global_store_short_d16_hi v140, v137, s[8:9]
	v_cvt_pk_bf16_f32 v138, v116, v117
	v_add_u32_e32 v139, 0x41400, v134
	v_add_u32_e32 v140, 0x41400, v135
	global_store_short v139, v138, s[8:9]
	global_store_short_d16_hi v140, v138, s[8:9]
	v_cvt_pk_bf16_f32 v137, v110, v111
	v_add_u32_e32 v139, 0xae000, v132
	v_add_u32_e32 v140, 0xae000, v133
	global_store_short v139, v137, s[8:9]
	global_store_short_d16_hi v140, v137, s[8:9]
	v_cvt_pk_bf16_f32 v138, v112, v113
	v_add_u32_e32 v139, 0xae000, v134
	v_add_u32_e32 v140, 0xae000, v135
	global_store_short v139, v138, s[8:9]
	global_store_short_d16_hi v140, v138, s[8:9]
	v_cvt_pk_bf16_f32 v137, v106, v107
	v_add_u32_e32 v139, 0xc3c00, v132
	v_add_u32_e32 v140, 0xc3c00, v133
	global_store_short v139, v137, s[8:9]
	global_store_short_d16_hi v140, v137, s[8:9]
	v_cvt_pk_bf16_f32 v138, v108, v109
	v_add_u32_e32 v139, 0xc3c00, v134
	v_add_u32_e32 v140, 0xc3c00, v135
	global_store_short v139, v138, s[8:9]
	global_store_short_d16_hi v140, v138, s[8:9]
	v_cvt_pk_bf16_f32 v137, v102, v103
	v_add_u32_e32 v139, 0xd9800, v132
	v_add_u32_e32 v140, 0xd9800, v133
	global_store_short v139, v137, s[8:9]
	global_store_short_d16_hi v140, v137, s[8:9]
	v_cvt_pk_bf16_f32 v138, v104, v105
	v_add_u32_e32 v139, 0xd9800, v134
	v_add_u32_e32 v140, 0xd9800, v135
	global_store_short v139, v138, s[8:9]
	global_store_short_d16_hi v140, v138, s[8:9]
	v_cvt_pk_bf16_f32 v137, v98, v99
	v_add_u32_e32 v139, 0xef400, v132
	v_add_u32_e32 v140, 0xef400, v133
	global_store_short v139, v137, s[8:9]
	global_store_short_d16_hi v140, v137, s[8:9]
	v_cvt_pk_bf16_f32 v138, v100, v101
	v_add_u32_e32 v139, 0xef400, v134
	v_add_u32_e32 v140, 0xef400, v135
	global_store_short v139, v138, s[8:9]
	global_store_short_d16_hi v140, v138, s[8:9]
	s_branch .Lipe0_done
.Lipe0_dq:
	v_mov_b32_e32 v146, v214
	s_branch .Lipe0_scaled
.Lipe0_sq:
	v_mov_b32_e32 v146, v215
.Lipe0_scaled:
	s_mul_i32 s10, s4, 0x15c0
	s_lshl_b32 s11, s25, 1
	s_add_u32 s10, s10, s11
	s_add_u32 s8, s50, s10
	s_addc_u32 s9, s51, 0
	v_mul_f32_e32 v126, v146, v126
	v_mul_f32_e32 v127, v146, v127
	v_cvt_pk_bf16_f32 v137, v126, v127
	global_store_short v132, v137, s[8:9]
	global_store_short_d16_hi v133, v137, s[8:9]
	v_mul_f32_e32 v128, v146, v128
	v_mul_f32_e32 v129, v146, v129
	v_cvt_pk_bf16_f32 v138, v128, v129
	global_store_short v134, v138, s[8:9]
	global_store_short_d16_hi v135, v138, s[8:9]
	v_mul_f32_e32 v122, v146, v122
	v_mul_f32_e32 v123, v146, v123
	v_cvt_pk_bf16_f32 v137, v122, v123
	v_add_u32_e32 v139, 0x15c00, v132
	v_add_u32_e32 v140, 0x15c00, v133
	global_store_short v139, v137, s[8:9]
	global_store_short_d16_hi v140, v137, s[8:9]
	v_mul_f32_e32 v124, v146, v124
	v_mul_f32_e32 v125, v146, v125
	v_cvt_pk_bf16_f32 v138, v124, v125
	v_add_u32_e32 v139, 0x15c00, v134
	v_add_u32_e32 v140, 0x15c00, v135
	global_store_short v139, v138, s[8:9]
	global_store_short_d16_hi v140, v138, s[8:9]
	v_mul_f32_e32 v118, v146, v118
	v_mul_f32_e32 v119, v146, v119
	v_cvt_pk_bf16_f32 v137, v118, v119
	v_add_u32_e32 v139, 0x2b800, v132
	v_add_u32_e32 v140, 0x2b800, v133
	global_store_short v139, v137, s[8:9]
	global_store_short_d16_hi v140, v137, s[8:9]
	v_mul_f32_e32 v120, v146, v120
	v_mul_f32_e32 v121, v146, v121
	v_cvt_pk_bf16_f32 v138, v120, v121
	v_add_u32_e32 v139, 0x2b800, v134
	v_add_u32_e32 v140, 0x2b800, v135
	global_store_short v139, v138, s[8:9]
	global_store_short_d16_hi v140, v138, s[8:9]
	v_mul_f32_e32 v114, v146, v114
	v_mul_f32_e32 v115, v146, v115
	v_cvt_pk_bf16_f32 v137, v114, v115
	v_add_u32_e32 v139, 0x41400, v132
; DI u16 f2bf(float x) { unsigned u = __float_as_uint(x); u += 0x7fffu + ((u >> 16) & 1u); return (u16)(u >> 16); }
; DI void phase_inproj(const Params& p, int layer, char* lds) {
;     ...
;         if (cw < DIN) {
;           float sc = 1.f;
;           if (col >= C_DQ && col < C_DK) sc = SC_DQ;
;           if (col >= C_SQ && col < C_SK) sc = SC_SQ;
;           const bool gate = col >= C_GATE;
; #pragma unroll
;           for (int ai = 0; ai < 2; ++ai)
; #pragma unroll
;             for (int m = 0; m < 4; ++m) {
; #pragma unroll
;               for (int j = 0; j < 4; ++j) {
;                 const int row = m0 + ai * 128 + wr8 * 64 + m * 16 + fq * 4 + j;
;                 float v = acc[ai][bj][m][n][j] * sc;
;                 if (gate) v = v * __builtin_amdgcn_rcpf(1.f + __expf(-v));
;                 dst[(size_t)row * dstr + fr] = f2bf(v);
;               }
	v_add_u32_e32 v140, 0x41400, v133
	global_store_short v139, v137, s[8:9]
	global_store_short_d16_hi v140, v137, s[8:9]
	v_mul_f32_e32 v116, v146, v116
	v_mul_f32_e32 v117, v146, v117
	v_cvt_pk_bf16_f32 v138, v116, v117
	v_add_u32_e32 v139, 0x41400, v134
	v_add_u32_e32 v140, 0x41400, v135
	global_store_short v139, v138, s[8:9]
	global_store_short_d16_hi v140, v138, s[8:9]
	v_mul_f32_e32 v110, v146, v110
	v_mul_f32_e32 v111, v146, v111
	v_cvt_pk_bf16_f32 v137, v110, v111
	v_add_u32_e32 v139, 0xae000, v132
	v_add_u32_e32 v140, 0xae000, v133
	global_store_short v139, v137, s[8:9]
	global_store_short_d16_hi v140, v137, s[8:9]
	v_mul_f32_e32 v112, v146, v112
	v_mul_f32_e32 v113, v146, v113
	v_cvt_pk_bf16_f32 v138, v112, v113
	v_add_u32_e32 v139, 0xae000, v134
	v_add_u32_e32 v140, 0xae000, v135
	global_store_short v139, v138, s[8:9]
	global_store_short_d16_hi v140, v138, s[8:9]
	v_mul_f32_e32 v106, v146, v106
	v_mul_f32_e32 v107, v146, v107
	v_cvt_pk_bf16_f32 v137, v106, v107
	v_add_u32_e32 v139, 0xc3c00, v132
	v_add_u32_e32 v140, 0xc3c00, v133
	global_store_short v139, v137, s[8:9]
	global_store_short_d16_hi v140, v137, s[8:9]
	v_mul_f32_e32 v108, v146, v108
	v_mul_f32_e32 v109, v146, v109
	v_cvt_pk_bf16_f32 v138, v108, v109
	v_add_u32_e32 v139, 0xc3c00, v134
	v_add_u32_e32 v140, 0xc3c00, v135
	global_store_short v139, v138, s[8:9]
	global_store_short_d16_hi v140, v138, s[8:9]
	v_mul_f32_e32 v102, v146, v102
	v_mul_f32_e32 v103, v146, v103
	v_cvt_pk_bf16_f32 v137, v102, v103
	v_add_u32_e32 v139, 0xd9800, v132
	v_add_u32_e32 v140, 0xd9800, v133
	global_store_short v139, v137, s[8:9]
	global_store_short_d16_hi v140, v137, s[8:9]
	v_mul_f32_e32 v104, v146, v104
	v_mul_f32_e32 v105, v146, v105
	v_cvt_pk_bf16_f32 v138, v104, v105
	v_add_u32_e32 v139, 0xd9800, v134
	v_add_u32_e32 v140, 0xd9800, v135
	global_store_short v139, v138, s[8:9]
	global_store_short_d16_hi v140, v138, s[8:9]
	v_mul_f32_e32 v98, v146, v98
	v_mul_f32_e32 v99, v146, v99
	v_cvt_pk_bf16_f32 v137, v98, v99
	v_add_u32_e32 v139, 0xef400, v132
	v_add_u32_e32 v140, 0xef400, v133
	global_store_short v139, v137, s[8:9]
	global_store_short_d16_hi v140, v137, s[8:9]
	v_mul_f32_e32 v100, v146, v100
	v_mul_f32_e32 v101, v146, v101
	v_cvt_pk_bf16_f32 v138, v100, v101
	v_add_u32_e32 v139, 0xef400, v134
	v_add_u32_e32 v140, 0xef400, v135
	global_store_short v139, v138, s[8:9]
	global_store_short_d16_hi v140, v138, s[8:9]
	s_branch .Lipe0_done
.Lipe0_gate:
	s_mul_i32 s10, s4, 0x15c0
	s_lshl_b32 s11, s25, 1
	s_add_u32 s10, s10, s11
	s_add_u32 s8, s50, s10
	s_addc_u32 s9, s51, 0
	v_mul_f32_e32 v141, 0xbfb8aa3b, v126
	v_mul_f32_e32 v142, 0xbfb8aa3b, v127
	v_exp_f32_e32 v141, v141
	v_exp_f32_e32 v142, v142
	v_add_f32_e32 v141, 1.0, v141
	v_add_f32_e32 v142, 1.0, v142
	v_rcp_f32_e32 v141, v141
	v_rcp_f32_e32 v142, v142
	v_mul_f32_e32 v126, v126, v141
	v_mul_f32_e32 v127, v127, v142
	v_cvt_pk_bf16_f32 v137, v126, v127
	global_store_short v132, v137, s[8:9]
	global_store_short_d16_hi v133, v137, s[8:9]
	v_mul_f32_e32 v143, 0xbfb8aa3b, v128
	v_mul_f32_e32 v145, 0xbfb8aa3b, v129
	v_exp_f32_e32 v143, v143
	v_exp_f32_e32 v145, v145
	v_add_f32_e32 v143, 1.0, v143
	v_add_f32_e32 v145, 1.0, v145
	v_rcp_f32_e32 v143, v143
	v_rcp_f32_e32 v145, v145
	v_mul_f32_e32 v128, v128, v143
	v_mul_f32_e32 v129, v129, v145
	v_cvt_pk_bf16_f32 v138, v128, v129
	global_store_short v134, v138, s[8:9]
	global_store_short_d16_hi v135, v138, s[8:9]
	v_mul_f32_e32 v141, 0xbfb8aa3b, v122
	v_mul_f32_e32 v142, 0xbfb8aa3b, v123
	v_exp_f32_e32 v141, v141
	v_exp_f32_e32 v142, v142
	v_add_f32_e32 v141, 1.0, v141
	v_add_f32_e32 v142, 1.0, v142
	v_rcp_f32_e32 v141, v141
	v_rcp_f32_e32 v142, v142
	v_mul_f32_e32 v122, v122, v141
	v_mul_f32_e32 v123, v123, v142
	v_cvt_pk_bf16_f32 v137, v122, v123
	v_add_u32_e32 v139, 0x15c00, v132
	v_add_u32_e32 v140, 0x15c00, v133
	global_store_short v139, v137, s[8:9]
	global_store_short_d16_hi v140, v137, s[8:9]
	v_mul_f32_e32 v143, 0xbfb8aa3b, v124
	v_mul_f32_e32 v145, 0xbfb8aa3b, v125
	v_exp_f32_e32 v143, v143
	v_exp_f32_e32 v145, v145
	v_add_f32_e32 v143, 1.0, v143
	v_add_f32_e32 v145, 1.0, v145
	v_rcp_f32_e32 v143, v143
	v_rcp_f32_e32 v145, v145
	v_mul_f32_e32 v124, v124, v143
	v_mul_f32_e32 v125, v125, v145
	v_cvt_pk_bf16_f32 v138, v124, v125
	v_add_u32_e32 v139, 0x15c00, v134
	v_add_u32_e32 v140, 0x15c00, v135
	global_store_short v139, v138, s[8:9]
	global_store_short_d16_hi v140, v138, s[8:9]
	v_mul_f32_e32 v141, 0xbfb8aa3b, v118
	v_mul_f32_e32 v142, 0xbfb8aa3b, v119
	v_exp_f32_e32 v141, v141
	v_exp_f32_e32 v142, v142
	v_add_f32_e32 v141, 1.0, v141
	v_add_f32_e32 v142, 1.0, v142
	v_rcp_f32_e32 v141, v141
	v_rcp_f32_e32 v142, v142
	v_mul_f32_e32 v118, v118, v141
	v_mul_f32_e32 v119, v119, v142
	v_cvt_pk_bf16_f32 v137, v118, v119
	v_add_u32_e32 v139, 0x2b800, v132
	v_add_u32_e32 v140, 0x2b800, v133
	global_store_short v139, v137, s[8:9]
	global_store_short_d16_hi v140, v137, s[8:9]
	v_mul_f32_e32 v143, 0xbfb8aa3b, v120
	v_mul_f32_e32 v145, 0xbfb8aa3b, v121
	v_exp_f32_e32 v143, v143
	v_exp_f32_e32 v145, v145
	v_add_f32_e32 v143, 1.0, v143
	v_add_f32_e32 v145, 1.0, v145
	v_rcp_f32_e32 v143, v143
	v_rcp_f32_e32 v145, v145
	v_mul_f32_e32 v120, v120, v143
	v_mul_f32_e32 v121, v121, v145
	v_cvt_pk_bf16_f32 v138, v120, v121
	v_add_u32_e32 v139, 0x2b800, v134
	v_add_u32_e32 v140, 0x2b800, v135
	global_store_short v139, v138, s[8:9]
	global_store_short_d16_hi v140, v138, s[8:9]
	v_mul_f32_e32 v141, 0xbfb8aa3b, v114
	v_mul_f32_e32 v142, 0xbfb8aa3b, v115
	v_exp_f32_e32 v141, v141
	v_exp_f32_e32 v142, v142
	v_add_f32_e32 v141, 1.0, v141
	v_add_f32_e32 v142, 1.0, v142
	v_rcp_f32_e32 v141, v141
	v_rcp_f32_e32 v142, v142
; DI u16 f2bf(float x) { unsigned u = __float_as_uint(x); u += 0x7fffu + ((u >> 16) & 1u); return (u16)(u >> 16); }
; DI void phase_inproj(const Params& p, int layer, char* lds) {
;     ...
;           const int bb = m0 / S;
;           if (cw >= C_DK && cw < C_DV) { const int o = cw - C_DK; dst = (u16*)(p.ws + OFF_DK) + ((size_t)(bb * 3 * S + (o >> 6) * S) << 6) + (o & 63); dstr = 64; }
;           else if (cw >= C_DV && cw < C_SQ) { const int o = cw - C_DV; dst = (u16*)(p.ws + OFF_DV) + ((size_t)(bb * 3 * S + (o >> 6) * S) << 6) + (o & 63); dstr = 64; }
;           else if (cw >= C_SK && cw < C_SV) { const int o = cw - C_SK; dst = (u16*)(p.ws + OFF_SK) + ((size_t)(bb * 1 * S + (o >> 6) * S) << 6) + (o & 63); dstr = 64; }
;           else if (cw >= C_SV && cw < C_GATE) { const int o = cw - C_SV; dst = (u16*)(p.ws + OFF_SV) + ((size_t)(bb * 1 * S + (o >> 6) * S) << 6) + (o & 63); dstr = 64; }
;         }
;         if (cw < DIN) {
;           float sc = 1.f;
;           if (col >= C_DQ && col < C_DK) sc = SC_DQ;
;           if (col >= C_SQ && col < C_SK) sc = SC_SQ;
;           const bool gate = col >= C_GATE;
; #pragma unroll
;           for (int ai = 0; ai < 2; ++ai)
; #pragma unroll
;             for (int m = 0; m < 4; ++m) {
; #pragma unroll
;               for (int j = 0; j < 4; ++j) {
;                 const int row = m0 + ai * 128 + wr8 * 64 + m * 16 + fq * 4 + j;
;                 float v = acc[ai][bj][m][n][j] * sc;
;                 if (gate) v = v * __builtin_amdgcn_rcpf(1.f + __expf(-v));
;                 dst[(size_t)row * dstr + fr] = f2bf(v);
;               }
	v_mul_f32_e32 v114, v114, v141
	v_mul_f32_e32 v115, v115, v142
	v_cvt_pk_bf16_f32 v137, v114, v115
	v_add_u32_e32 v139, 0x41400, v132
	v_add_u32_e32 v140, 0x41400, v133
	global_store_short v139, v137, s[8:9]
	global_store_short_d16_hi v140, v137, s[8:9]
	v_mul_f32_e32 v143, 0xbfb8aa3b, v116
	v_mul_f32_e32 v145, 0xbfb8aa3b, v117
	v_exp_f32_e32 v143, v143
	v_exp_f32_e32 v145, v145
	v_add_f32_e32 v143, 1.0, v143
	v_add_f32_e32 v145, 1.0, v145
	v_rcp_f32_e32 v143, v143
	v_rcp_f32_e32 v145, v145
	v_mul_f32_e32 v116, v116, v143
	v_mul_f32_e32 v117, v117, v145
	v_cvt_pk_bf16_f32 v138, v116, v117
	v_add_u32_e32 v139, 0x41400, v134
	v_add_u32_e32 v140, 0x41400, v135
	global_store_short v139, v138, s[8:9]
	global_store_short_d16_hi v140, v138, s[8:9]
	v_mul_f32_e32 v141, 0xbfb8aa3b, v110
	v_mul_f32_e32 v142, 0xbfb8aa3b, v111
	v_exp_f32_e32 v141, v141
	v_exp_f32_e32 v142, v142
	v_add_f32_e32 v141, 1.0, v141
	v_add_f32_e32 v142, 1.0, v142
	v_rcp_f32_e32 v141, v141
	v_rcp_f32_e32 v142, v142
	v_mul_f32_e32 v110, v110, v141
	v_mul_f32_e32 v111, v111, v142
	v_cvt_pk_bf16_f32 v137, v110, v111
	v_add_u32_e32 v139, 0xae000, v132
	v_add_u32_e32 v140, 0xae000, v133
	global_store_short v139, v137, s[8:9]
	global_store_short_d16_hi v140, v137, s[8:9]
	v_mul_f32_e32 v143, 0xbfb8aa3b, v112
	v_mul_f32_e32 v145, 0xbfb8aa3b, v113
	v_exp_f32_e32 v143, v143
	v_exp_f32_e32 v145, v145
	v_add_f32_e32 v143, 1.0, v143
	v_add_f32_e32 v145, 1.0, v145
	v_rcp_f32_e32 v143, v143
	v_rcp_f32_e32 v145, v145
	v_mul_f32_e32 v112, v112, v143
	v_mul_f32_e32 v113, v113, v145
	v_cvt_pk_bf16_f32 v138, v112, v113
	v_add_u32_e32 v139, 0xae000, v134
	v_add_u32_e32 v140, 0xae000, v135
	global_store_short v139, v138, s[8:9]
	global_store_short_d16_hi v140, v138, s[8:9]
	v_mul_f32_e32 v141, 0xbfb8aa3b, v106
	v_mul_f32_e32 v142, 0xbfb8aa3b, v107
	v_exp_f32_e32 v141, v141
	v_exp_f32_e32 v142, v142
	v_add_f32_e32 v141, 1.0, v141
	v_add_f32_e32 v142, 1.0, v142
	v_rcp_f32_e32 v141, v141
	v_rcp_f32_e32 v142, v142
	v_mul_f32_e32 v106, v106, v141
	v_mul_f32_e32 v107, v107, v142
	v_cvt_pk_bf16_f32 v137, v106, v107
	v_add_u32_e32 v139, 0xc3c00, v132
	v_add_u32_e32 v140, 0xc3c00, v133
	global_store_short v139, v137, s[8:9]
	global_store_short_d16_hi v140, v137, s[8:9]
	v_mul_f32_e32 v143, 0xbfb8aa3b, v108
	v_mul_f32_e32 v145, 0xbfb8aa3b, v109
	v_exp_f32_e32 v143, v143
	v_exp_f32_e32 v145, v145
	v_add_f32_e32 v143, 1.0, v143
	v_add_f32_e32 v145, 1.0, v145
	v_rcp_f32_e32 v143, v143
	v_rcp_f32_e32 v145, v145
	v_mul_f32_e32 v108, v108, v143
	v_mul_f32_e32 v109, v109, v145
	v_cvt_pk_bf16_f32 v138, v108, v109
	v_add_u32_e32 v139, 0xc3c00, v134
	v_add_u32_e32 v140, 0xc3c00, v135
	global_store_short v139, v138, s[8:9]
	global_store_short_d16_hi v140, v138, s[8:9]
	v_mul_f32_e32 v141, 0xbfb8aa3b, v102
	v_mul_f32_e32 v142, 0xbfb8aa3b, v103
	v_exp_f32_e32 v141, v141
	v_exp_f32_e32 v142, v142
	v_add_f32_e32 v141, 1.0, v141
	v_add_f32_e32 v142, 1.0, v142
	v_rcp_f32_e32 v141, v141
	v_rcp_f32_e32 v142, v142
	v_mul_f32_e32 v102, v102, v141
	v_mul_f32_e32 v103, v103, v142
	v_cvt_pk_bf16_f32 v137, v102, v103
	v_add_u32_e32 v139, 0xd9800, v132
	v_add_u32_e32 v140, 0xd9800, v133
	global_store_short v139, v137, s[8:9]
	global_store_short_d16_hi v140, v137, s[8:9]
	v_mul_f32_e32 v143, 0xbfb8aa3b, v104
	v_mul_f32_e32 v145, 0xbfb8aa3b, v105
	v_exp_f32_e32 v143, v143
	v_exp_f32_e32 v145, v145
	v_add_f32_e32 v143, 1.0, v143
	v_add_f32_e32 v145, 1.0, v145
	v_rcp_f32_e32 v143, v143
	v_rcp_f32_e32 v145, v145
	v_mul_f32_e32 v104, v104, v143
	v_mul_f32_e32 v105, v105, v145
	v_cvt_pk_bf16_f32 v138, v104, v105
	v_add_u32_e32 v139, 0xd9800, v134
	v_add_u32_e32 v140, 0xd9800, v135
	global_store_short v139, v138, s[8:9]
	global_store_short_d16_hi v140, v138, s[8:9]
	v_mul_f32_e32 v141, 0xbfb8aa3b, v98
	v_mul_f32_e32 v142, 0xbfb8aa3b, v99
	v_exp_f32_e32 v141, v141
	v_exp_f32_e32 v142, v142
	v_add_f32_e32 v141, 1.0, v141
	v_add_f32_e32 v142, 1.0, v142
	v_rcp_f32_e32 v141, v141
	v_rcp_f32_e32 v142, v142
	v_mul_f32_e32 v98, v98, v141
	v_mul_f32_e32 v99, v99, v142
	v_cvt_pk_bf16_f32 v137, v98, v99
	v_add_u32_e32 v139, 0xef400, v132
	v_add_u32_e32 v140, 0xef400, v133
	global_store_short v139, v137, s[8:9]
	global_store_short_d16_hi v140, v137, s[8:9]
	v_mul_f32_e32 v143, 0xbfb8aa3b, v100
	v_mul_f32_e32 v145, 0xbfb8aa3b, v101
	v_exp_f32_e32 v143, v143
	v_exp_f32_e32 v145, v145
	v_add_f32_e32 v143, 1.0, v143
	v_add_f32_e32 v145, 1.0, v145
	v_rcp_f32_e32 v143, v143
	v_rcp_f32_e32 v145, v145
	v_mul_f32_e32 v100, v100, v143
	v_mul_f32_e32 v101, v101, v145
	v_cvt_pk_bf16_f32 v138, v100, v101
	v_add_u32_e32 v139, 0xef400, v134
	v_add_u32_e32 v140, 0xef400, v135
	global_store_short v139, v138, s[8:9]
	global_store_short_d16_hi v140, v138, s[8:9]
	s_branch .Lipe0_done
.Lipe0_dk:
	s_sub_u32 s10, s25, 608
	s_and_b32 s11, s10, 63
	s_lshr_b32 s10, s10, 6
	s_lshl_b32 s10, s10, 13
	s_add_u32 s10, s10, s4
	s_mul_i32 s5, s27, 24576
	s_add_u32 s10, s10, s5
	s_lshl_b32 s10, s10, 7
	s_lshl_b32 s11, s11, 1
	s_add_u32 s10, s10, s11
	v_readlane_b32 s8, v254, 41
	v_readlane_b32 s9, v254, 42
	s_add_u32 s8, s8, s10
	s_addc_u32 s9, s9, 0
	s_branch .Lipe0_kv
.Lipe0_dv:
	s_sub_u32 s10, s25, 864
	s_and_b32 s11, s10, 63
	s_lshr_b32 s10, s10, 6
	s_lshl_b32 s10, s10, 13
	s_add_u32 s10, s10, s4
	s_mul_i32 s5, s27, 24576
	s_add_u32 s10, s10, s5
	s_lshl_b32 s10, s10, 7
	s_lshl_b32 s11, s11, 1
	s_add_u32 s10, s10, s11
	v_readlane_b32 s8, v254, 39
	v_readlane_b32 s9, v254, 40
	s_add_u32 s8, s8, s10
	s_addc_u32 s9, s9, 0
	s_branch .Lipe0_kv
; DI u16 f2bf(float x) { unsigned u = __float_as_uint(x); u += 0x7fffu + ((u >> 16) & 1u); return (u16)(u >> 16); }
; DI void phase_inproj(const Params& p, int layer, char* lds) {
;     ...
;           else if (cw >= C_SK && cw < C_SV) { const int o = cw - C_SK; dst = (u16*)(p.ws + OFF_SK) + ((size_t)(bb * 1 * S + (o >> 6) * S) << 6) + (o & 63); dstr = 64; }
;           else if (cw >= C_SV && cw < C_GATE) { const int o = cw - C_SV; dst = (u16*)(p.ws + OFF_SV) + ((size_t)(bb * 1 * S + (o >> 6) * S) << 6) + (o & 63); dstr = 64; }
;         }
;         if (cw < DIN) {
;           float sc = 1.f;
;           if (col >= C_DQ && col < C_DK) sc = SC_DQ;
;           if (col >= C_SQ && col < C_SK) sc = SC_SQ;
;           const bool gate = col >= C_GATE;
; #pragma unroll
;           for (int ai = 0; ai < 2; ++ai)
; #pragma unroll
;             for (int m = 0; m < 4; ++m) {
; #pragma unroll
;               for (int j = 0; j < 4; ++j) {
;                 const int row = m0 + ai * 128 + wr8 * 64 + m * 16 + fq * 4 + j;
;                 float v = acc[ai][bj][m][n][j] * sc;
;                 if (gate) v = v * __builtin_amdgcn_rcpf(1.f + __expf(-v));
;                 dst[(size_t)row * dstr + fr] = f2bf(v);
;               }
;               __builtin_amdgcn_sched_barrier(0);
;             }
;         }
.Lipe0_sk:
	s_sub_u32 s10, s25, 1504
	s_and_b32 s11, s10, 63
	s_lshr_b32 s10, s10, 6
	s_lshl_b32 s10, s10, 13
	s_add_u32 s10, s10, s4
	s_mul_i32 s5, s27, 8192
	s_add_u32 s10, s10, s5
	s_lshl_b32 s10, s10, 7
	s_lshl_b32 s11, s11, 1
	s_add_u32 s10, s10, s11
	v_readlane_b32 s8, v254, 37
	v_readlane_b32 s9, v254, 38
	s_add_u32 s8, s8, s10
	s_addc_u32 s9, s9, 0
	s_branch .Lipe0_kv
.Lipe0_sv:
	s_sub_u32 s10, s25, 1632
	s_and_b32 s11, s10, 63
	s_lshr_b32 s10, s10, 6
	s_lshl_b32 s10, s10, 13
	s_add_u32 s10, s10, s4
	s_mul_i32 s5, s27, 8192
	s_add_u32 s10, s10, s5
	s_lshl_b32 s10, s10, 7
	s_lshl_b32 s11, s11, 1
	s_add_u32 s10, s10, s11
	v_readlane_b32 s8, v254, 35
	v_readlane_b32 s9, v254, 36
	s_add_u32 s8, s8, s10
	s_addc_u32 s9, s9, 0
.Lipe0_kv:
	v_cvt_pk_bf16_f32 v137, v126, v127
	global_store_short v136, v137, s[8:9] offset:0
	global_store_short_d16_hi v136, v137, s[8:9] offset:128
	v_cvt_pk_bf16_f32 v138, v128, v129
	global_store_short v136, v138, s[8:9] offset:256
	global_store_short_d16_hi v136, v138, s[8:9] offset:384
	v_add_u32_e32 v139, 0x800, v136
	v_cvt_pk_bf16_f32 v137, v122, v123
	global_store_short v139, v137, s[8:9] offset:0
	global_store_short_d16_hi v139, v137, s[8:9] offset:128
	v_cvt_pk_bf16_f32 v138, v124, v125
	global_store_short v139, v138, s[8:9] offset:256
	global_store_short_d16_hi v139, v138, s[8:9] offset:384
	v_add_u32_e32 v139, 0x1000, v136
	v_cvt_pk_bf16_f32 v137, v118, v119
	global_store_short v139, v137, s[8:9] offset:0
	global_store_short_d16_hi v139, v137, s[8:9] offset:128
	v_cvt_pk_bf16_f32 v138, v120, v121
	global_store_short v139, v138, s[8:9] offset:256
	global_store_short_d16_hi v139, v138, s[8:9] offset:384
	v_add_u32_e32 v139, 0x1800, v136
	v_cvt_pk_bf16_f32 v137, v114, v115
	global_store_short v139, v137, s[8:9] offset:0
	global_store_short_d16_hi v139, v137, s[8:9] offset:128
	v_cvt_pk_bf16_f32 v138, v116, v117
	global_store_short v139, v138, s[8:9] offset:256
	global_store_short_d16_hi v139, v138, s[8:9] offset:384
	v_add_u32_e32 v139, 0x4000, v136
	v_cvt_pk_bf16_f32 v137, v110, v111
	global_store_short v139, v137, s[8:9] offset:0
	global_store_short_d16_hi v139, v137, s[8:9] offset:128
	v_cvt_pk_bf16_f32 v138, v112, v113
	global_store_short v139, v138, s[8:9] offset:256
	global_store_short_d16_hi v139, v138, s[8:9] offset:384
	v_add_u32_e32 v139, 0x4800, v136
	v_cvt_pk_bf16_f32 v137, v106, v107
	global_store_short v139, v137, s[8:9] offset:0
	global_store_short_d16_hi v139, v137, s[8:9] offset:128
	v_cvt_pk_bf16_f32 v138, v108, v109
	global_store_short v139, v138, s[8:9] offset:256
	global_store_short_d16_hi v139, v138, s[8:9] offset:384
	v_add_u32_e32 v139, 0x5000, v136
	v_cvt_pk_bf16_f32 v137, v102, v103
	global_store_short v139, v137, s[8:9] offset:0
	global_store_short_d16_hi v139, v137, s[8:9] offset:128
	v_cvt_pk_bf16_f32 v138, v104, v105
	global_store_short v139, v138, s[8:9] offset:256
	global_store_short_d16_hi v139, v138, s[8:9] offset:384
	v_add_u32_e32 v139, 0x5800, v136
	v_cvt_pk_bf16_f32 v137, v98, v99
	global_store_short v139, v137, s[8:9] offset:0
	global_store_short_d16_hi v139, v137, s[8:9] offset:128
	v_cvt_pk_bf16_f32 v138, v100, v101
	global_store_short v139, v138, s[8:9] offset:256
	global_store_short_d16_hi v139, v138, s[8:9] offset:384
.Lipe0_done:
	s_add_u32 s25, s6, s26
	s_add_u32 s25, s25, 16
	s_cmpk_ge_u32 s25, 2784
	s_cbranch_scc1 .Lipe1_done
	s_cmpk_ge_u32 s25, 1760
	s_cbranch_scc1 .Lipe1_gate
	s_cmpk_ge_u32 s25, 1632
	s_cbranch_scc1 .Lipe1_sv
	s_cmpk_ge_u32 s25, 1504
	s_cbranch_scc1 .Lipe1_sk
	s_cmpk_ge_u32 s25, 1120
	s_cbranch_scc1 .Lipe1_sq
	s_cmpk_ge_u32 s25, 864
	s_cbranch_scc1 .Lipe1_dv
	s_cmpk_ge_u32 s25, 608
	s_cbranch_scc1 .Lipe1_dk
	s_cmpk_ge_u32 s25, 352
	s_cbranch_scc1 .Lipe1_dq
	s_mul_i32 s10, s4, 0x15c0
	s_lshl_b32 s11, s25, 1
	s_add_u32 s10, s10, s11
	s_add_u32 s8, s50, s10
	s_addc_u32 s9, s51, 0
	v_cvt_pk_bf16_f32 v137, v94, v95
	global_store_short v132, v137, s[8:9]
	global_store_short_d16_hi v133, v137, s[8:9]
	v_cvt_pk_bf16_f32 v138, v96, v97
	global_store_short v134, v138, s[8:9]
	global_store_short_d16_hi v135, v138, s[8:9]
	v_cvt_pk_bf16_f32 v137, v90, v91
	v_add_u32_e32 v139, 0x15c00, v132
	v_add_u32_e32 v140, 0x15c00, v133
	global_store_short v139, v137, s[8:9]
	global_store_short_d16_hi v140, v137, s[8:9]
	v_cvt_pk_bf16_f32 v138, v92, v93
	v_add_u32_e32 v139, 0x15c00, v134
	v_add_u32_e32 v140, 0x15c00, v135
	global_store_short v139, v138, s[8:9]
	global_store_short_d16_hi v140, v138, s[8:9]
	v_cvt_pk_bf16_f32 v137, v86, v87
	v_add_u32_e32 v139, 0x2b800, v132
	v_add_u32_e32 v140, 0x2b800, v133
	global_store_short v139, v137, s[8:9]
	global_store_short_d16_hi v140, v137, s[8:9]
	v_cvt_pk_bf16_f32 v138, v88, v89
	v_add_u32_e32 v139, 0x2b800, v134
	v_add_u32_e32 v140, 0x2b800, v135
	global_store_short v139, v138, s[8:9]
	global_store_short_d16_hi v140, v138, s[8:9]
	v_cvt_pk_bf16_f32 v137, v82, v83
	v_add_u32_e32 v139, 0x41400, v132
	v_add_u32_e32 v140, 0x41400, v133
	global_store_short v139, v137, s[8:9]
	global_store_short_d16_hi v140, v137, s[8:9]
	v_cvt_pk_bf16_f32 v138, v84, v85
	v_add_u32_e32 v139, 0x41400, v134
	v_add_u32_e32 v140, 0x41400, v135
	global_store_short v139, v138, s[8:9]
	global_store_short_d16_hi v140, v138, s[8:9]
	v_cvt_pk_bf16_f32 v137, v78, v79
	v_add_u32_e32 v139, 0xae000, v132
	v_add_u32_e32 v140, 0xae000, v133
	global_store_short v139, v137, s[8:9]
	global_store_short_d16_hi v140, v137, s[8:9]
	v_cvt_pk_bf16_f32 v138, v80, v81
	v_add_u32_e32 v139, 0xae000, v134
	v_add_u32_e32 v140, 0xae000, v135
	global_store_short v139, v138, s[8:9]
	global_store_short_d16_hi v140, v138, s[8:9]
	v_cvt_pk_bf16_f32 v137, v74, v75
	v_add_u32_e32 v139, 0xc3c00, v132
	v_add_u32_e32 v140, 0xc3c00, v133
	global_store_short v139, v137, s[8:9]
	global_store_short_d16_hi v140, v137, s[8:9]
	v_cvt_pk_bf16_f32 v138, v76, v77
	v_add_u32_e32 v139, 0xc3c00, v134
	v_add_u32_e32 v140, 0xc3c00, v135
	global_store_short v139, v138, s[8:9]
	global_store_short_d16_hi v140, v138, s[8:9]
	v_cvt_pk_bf16_f32 v137, v70, v71
	v_add_u32_e32 v139, 0xd9800, v132
	v_add_u32_e32 v140, 0xd9800, v133
	global_store_short v139, v137, s[8:9]
	global_store_short_d16_hi v140, v137, s[8:9]
	v_cvt_pk_bf16_f32 v138, v72, v73
	v_add_u32_e32 v139, 0xd9800, v134
	v_add_u32_e32 v140, 0xd9800, v135
	global_store_short v139, v138, s[8:9]
	global_store_short_d16_hi v140, v138, s[8:9]
	v_cvt_pk_bf16_f32 v137, v66, v67
	v_add_u32_e32 v139, 0xef400, v132
	v_add_u32_e32 v140, 0xef400, v133
	global_store_short v139, v137, s[8:9]
	global_store_short_d16_hi v140, v137, s[8:9]
	v_cvt_pk_bf16_f32 v138, v68, v69
	v_add_u32_e32 v139, 0xef400, v134
	v_add_u32_e32 v140, 0xef400, v135
	global_store_short v139, v138, s[8:9]
	global_store_short_d16_hi v140, v138, s[8:9]
	s_branch .Lipe1_done

; DI u16 f2bf(float x) { unsigned u = __float_as_uint(x); u += 0x7fffu + ((u >> 16) & 1u); return (u16)(u >> 16); }
; DI void phase_inproj(const Params& p, int layer, char* lds) {
;     ...
;         if (cw < DIN) {
;           float sc = 1.f;
;           if (col >= C_DQ && col < C_DK) sc = SC_DQ;
;           if (col >= C_SQ && col < C_SK) sc = SC_SQ;
;           const bool gate = col >= C_GATE;
; #pragma unroll
;           for (int ai = 0; ai < 2; ++ai)
; #pragma unroll
;             for (int m = 0; m < 4; ++m) {
; #pragma unroll
;               for (int j = 0; j < 4; ++j) {
;                 const int row = m0 + ai * 128 + wr8 * 64 + m * 16 + fq * 4 + j;
;                 float v = acc[ai][bj][m][n][j] * sc;
;                 if (gate) v = v * __builtin_amdgcn_rcpf(1.f + __expf(-v));
;                 dst[(size_t)row * dstr + fr] = f2bf(v);
;               }
.Lipe1_scaled:
	s_mul_i32 s10, s4, 0x15c0
	s_lshl_b32 s11, s25, 1
	s_add_u32 s10, s10, s11
	s_add_u32 s8, s50, s10
	s_addc_u32 s9, s51, 0
	v_mul_f32_e32 v94, v146, v94
	v_mul_f32_e32 v95, v146, v95
	v_cvt_pk_bf16_f32 v137, v94, v95
	global_store_short v132, v137, s[8:9]
	global_store_short_d16_hi v133, v137, s[8:9]
	v_mul_f32_e32 v96, v146, v96
	v_mul_f32_e32 v97, v146, v97
	v_cvt_pk_bf16_f32 v138, v96, v97
	global_store_short v134, v138, s[8:9]
	global_store_short_d16_hi v135, v138, s[8:9]
	v_mul_f32_e32 v90, v146, v90
	v_mul_f32_e32 v91, v146, v91
	v_cvt_pk_bf16_f32 v137, v90, v91
	v_add_u32_e32 v139, 0x15c00, v132
	v_add_u32_e32 v140, 0x15c00, v133
	global_store_short v139, v137, s[8:9]
	global_store_short_d16_hi v140, v137, s[8:9]
	v_mul_f32_e32 v92, v146, v92
	v_mul_f32_e32 v93, v146, v93
	v_cvt_pk_bf16_f32 v138, v92, v93
	v_add_u32_e32 v139, 0x15c00, v134
	v_add_u32_e32 v140, 0x15c00, v135
	global_store_short v139, v138, s[8:9]
	global_store_short_d16_hi v140, v138, s[8:9]
	v_mul_f32_e32 v86, v146, v86
	v_mul_f32_e32 v87, v146, v87
	v_cvt_pk_bf16_f32 v137, v86, v87
	v_add_u32_e32 v139, 0x2b800, v132
	v_add_u32_e32 v140, 0x2b800, v133
	global_store_short v139, v137, s[8:9]
	global_store_short_d16_hi v140, v137, s[8:9]
	v_mul_f32_e32 v88, v146, v88
	v_mul_f32_e32 v89, v146, v89
	v_cvt_pk_bf16_f32 v138, v88, v89
	v_add_u32_e32 v139, 0x2b800, v134
	v_add_u32_e32 v140, 0x2b800, v135
	global_store_short v139, v138, s[8:9]
	global_store_short_d16_hi v140, v138, s[8:9]
	v_mul_f32_e32 v82, v146, v82
	v_mul_f32_e32 v83, v146, v83
	v_cvt_pk_bf16_f32 v137, v82, v83
	v_add_u32_e32 v139, 0x41400, v132
	v_add_u32_e32 v140, 0x41400, v133
	global_store_short v139, v137, s[8:9]
	global_store_short_d16_hi v140, v137, s[8:9]
	v_mul_f32_e32 v84, v146, v84
	v_mul_f32_e32 v85, v146, v85
	v_cvt_pk_bf16_f32 v138, v84, v85
	v_add_u32_e32 v139, 0x41400, v134
	v_add_u32_e32 v140, 0x41400, v135
	global_store_short v139, v138, s[8:9]
	global_store_short_d16_hi v140, v138, s[8:9]
	v_mul_f32_e32 v78, v146, v78
	v_mul_f32_e32 v79, v146, v79
	v_cvt_pk_bf16_f32 v137, v78, v79
	v_add_u32_e32 v139, 0xae000, v132
	v_add_u32_e32 v140, 0xae000, v133
	global_store_short v139, v137, s[8:9]
	global_store_short_d16_hi v140, v137, s[8:9]
	v_mul_f32_e32 v80, v146, v80
	v_mul_f32_e32 v81, v146, v81
	v_cvt_pk_bf16_f32 v138, v80, v81
	v_add_u32_e32 v139, 0xae000, v134
	v_add_u32_e32 v140, 0xae000, v135
	global_store_short v139, v138, s[8:9]
	global_store_short_d16_hi v140, v138, s[8:9]
	v_mul_f32_e32 v74, v146, v74
	v_mul_f32_e32 v75, v146, v75
	v_cvt_pk_bf16_f32 v137, v74, v75
	v_add_u32_e32 v139, 0xc3c00, v132
	v_add_u32_e32 v140, 0xc3c00, v133
	global_store_short v139, v137, s[8:9]
	global_store_short_d16_hi v140, v137, s[8:9]
	v_mul_f32_e32 v76, v146, v76
	v_mul_f32_e32 v77, v146, v77
	v_cvt_pk_bf16_f32 v138, v76, v77
	v_add_u32_e32 v139, 0xc3c00, v134
	v_add_u32_e32 v140, 0xc3c00, v135
	global_store_short v139, v138, s[8:9]
	global_store_short_d16_hi v140, v138, s[8:9]
	v_mul_f32_e32 v70, v146, v70
	v_mul_f32_e32 v71, v146, v71
	v_cvt_pk_bf16_f32 v137, v70, v71
	v_add_u32_e32 v139, 0xd9800, v132
	v_add_u32_e32 v140, 0xd9800, v133
	global_store_short v139, v137, s[8:9]
	global_store_short_d16_hi v140, v137, s[8:9]
	v_mul_f32_e32 v72, v146, v72
	v_mul_f32_e32 v73, v146, v73
	v_cvt_pk_bf16_f32 v138, v72, v73
	v_add_u32_e32 v139, 0xd9800, v134
	v_add_u32_e32 v140, 0xd9800, v135
	global_store_short v139, v138, s[8:9]
	global_store_short_d16_hi v140, v138, s[8:9]
	v_mul_f32_e32 v66, v146, v66
	v_mul_f32_e32 v67, v146, v67
	v_cvt_pk_bf16_f32 v137, v66, v67
	v_add_u32_e32 v139, 0xef400, v132
	v_add_u32_e32 v140, 0xef400, v133
	global_store_short v139, v137, s[8:9]
	global_store_short_d16_hi v140, v137, s[8:9]
	v_mul_f32_e32 v68, v146, v68
	v_mul_f32_e32 v69, v146, v69
	v_cvt_pk_bf16_f32 v138, v68, v69
	v_add_u32_e32 v139, 0xef400, v134
	v_add_u32_e32 v140, 0xef400, v135
	global_store_short v139, v138, s[8:9]
	global_store_short_d16_hi v140, v138, s[8:9]
	s_branch .Lipe1_done
.Lipe1_gate:
	s_mul_i32 s10, s4, 0x15c0
	s_lshl_b32 s11, s25, 1
	s_add_u32 s10, s10, s11
	s_add_u32 s8, s50, s10
	s_addc_u32 s9, s51, 0
	v_mul_f32_e32 v141, 0xbfb8aa3b, v94
	v_mul_f32_e32 v142, 0xbfb8aa3b, v95
	v_exp_f32_e32 v141, v141
	v_exp_f32_e32 v142, v142
	v_add_f32_e32 v141, 1.0, v141
	v_add_f32_e32 v142, 1.0, v142
	v_rcp_f32_e32 v141, v141
	v_rcp_f32_e32 v142, v142
	v_mul_f32_e32 v94, v94, v141
	v_mul_f32_e32 v95, v95, v142
	v_cvt_pk_bf16_f32 v137, v94, v95
	global_store_short v132, v137, s[8:9]
	global_store_short_d16_hi v133, v137, s[8:9]
	v_mul_f32_e32 v143, 0xbfb8aa3b, v96
	v_mul_f32_e32 v145, 0xbfb8aa3b, v97
	v_exp_f32_e32 v143, v143
	v_exp_f32_e32 v145, v145
	v_add_f32_e32 v143, 1.0, v143
	v_add_f32_e32 v145, 1.0, v145
	v_rcp_f32_e32 v143, v143
	v_rcp_f32_e32 v145, v145
	v_mul_f32_e32 v96, v96, v143
	v_mul_f32_e32 v97, v97, v145
	v_cvt_pk_bf16_f32 v138, v96, v97
	global_store_short v134, v138, s[8:9]
	global_store_short_d16_hi v135, v138, s[8:9]
	v_mul_f32_e32 v141, 0xbfb8aa3b, v90
	v_mul_f32_e32 v142, 0xbfb8aa3b, v91
	v_exp_f32_e32 v141, v141
	v_exp_f32_e32 v142, v142
	v_add_f32_e32 v141, 1.0, v141
	v_add_f32_e32 v142, 1.0, v142
	v_rcp_f32_e32 v141, v141
	v_rcp_f32_e32 v142, v142
	v_mul_f32_e32 v90, v90, v141
	v_mul_f32_e32 v91, v91, v142
	v_cvt_pk_bf16_f32 v137, v90, v91
	v_add_u32_e32 v139, 0x15c00, v132
	v_add_u32_e32 v140, 0x15c00, v133
	global_store_short v139, v137, s[8:9]
	global_store_short_d16_hi v140, v137, s[8:9]
	v_mul_f32_e32 v143, 0xbfb8aa3b, v92
	v_mul_f32_e32 v145, 0xbfb8aa3b, v93
	v_exp_f32_e32 v143, v143
	v_exp_f32_e32 v145, v145
	v_add_f32_e32 v143, 1.0, v143
	v_add_f32_e32 v145, 1.0, v145
; DI u16 f2bf(float x) { unsigned u = __float_as_uint(x); u += 0x7fffu + ((u >> 16) & 1u); return (u16)(u >> 16); }
; DI void phase_inproj(const Params& p, int layer, char* lds) {
;     ...
;         if (cw < DIN) {
;           float sc = 1.f;
;           if (col >= C_DQ && col < C_DK) sc = SC_DQ;
;           if (col >= C_SQ && col < C_SK) sc = SC_SQ;
;           const bool gate = col >= C_GATE;
; #pragma unroll
;           for (int ai = 0; ai < 2; ++ai)
; #pragma unroll
;             for (int m = 0; m < 4; ++m) {
; #pragma unroll
;               for (int j = 0; j < 4; ++j) {
;                 const int row = m0 + ai * 128 + wr8 * 64 + m * 16 + fq * 4 + j;
;                 float v = acc[ai][bj][m][n][j] * sc;
;                 if (gate) v = v * __builtin_amdgcn_rcpf(1.f + __expf(-v));
;                 dst[(size_t)row * dstr + fr] = f2bf(v);
;               }
	v_rcp_f32_e32 v143, v143
	v_rcp_f32_e32 v145, v145
	v_mul_f32_e32 v92, v92, v143
	v_mul_f32_e32 v93, v93, v145
	v_cvt_pk_bf16_f32 v138, v92, v93
	v_add_u32_e32 v139, 0x15c00, v134
	v_add_u32_e32 v140, 0x15c00, v135
	global_store_short v139, v138, s[8:9]
	global_store_short_d16_hi v140, v138, s[8:9]
	v_mul_f32_e32 v141, 0xbfb8aa3b, v86
	v_mul_f32_e32 v142, 0xbfb8aa3b, v87
	v_exp_f32_e32 v141, v141
	v_exp_f32_e32 v142, v142
	v_add_f32_e32 v141, 1.0, v141
	v_add_f32_e32 v142, 1.0, v142
	v_rcp_f32_e32 v141, v141
	v_rcp_f32_e32 v142, v142
	v_mul_f32_e32 v86, v86, v141
	v_mul_f32_e32 v87, v87, v142
	v_cvt_pk_bf16_f32 v137, v86, v87
	v_add_u32_e32 v139, 0x2b800, v132
	v_add_u32_e32 v140, 0x2b800, v133
	global_store_short v139, v137, s[8:9]
	global_store_short_d16_hi v140, v137, s[8:9]
	v_mul_f32_e32 v143, 0xbfb8aa3b, v88
	v_mul_f32_e32 v145, 0xbfb8aa3b, v89
	v_exp_f32_e32 v143, v143
	v_exp_f32_e32 v145, v145
	v_add_f32_e32 v143, 1.0, v143
	v_add_f32_e32 v145, 1.0, v145
	v_rcp_f32_e32 v143, v143
	v_rcp_f32_e32 v145, v145
	v_mul_f32_e32 v88, v88, v143
	v_mul_f32_e32 v89, v89, v145
	v_cvt_pk_bf16_f32 v138, v88, v89
	v_add_u32_e32 v139, 0x2b800, v134
	v_add_u32_e32 v140, 0x2b800, v135
	global_store_short v139, v138, s[8:9]
	global_store_short_d16_hi v140, v138, s[8:9]
	v_mul_f32_e32 v141, 0xbfb8aa3b, v82
	v_mul_f32_e32 v142, 0xbfb8aa3b, v83
	v_exp_f32_e32 v141, v141
	v_exp_f32_e32 v142, v142
	v_add_f32_e32 v141, 1.0, v141
	v_add_f32_e32 v142, 1.0, v142
	v_rcp_f32_e32 v141, v141
	v_rcp_f32_e32 v142, v142
	v_mul_f32_e32 v82, v82, v141
	v_mul_f32_e32 v83, v83, v142
	v_cvt_pk_bf16_f32 v137, v82, v83
	v_add_u32_e32 v139, 0x41400, v132
	v_add_u32_e32 v140, 0x41400, v133
	global_store_short v139, v137, s[8:9]
	global_store_short_d16_hi v140, v137, s[8:9]
	v_mul_f32_e32 v143, 0xbfb8aa3b, v84
	v_mul_f32_e32 v145, 0xbfb8aa3b, v85
	v_exp_f32_e32 v143, v143
	v_exp_f32_e32 v145, v145
	v_add_f32_e32 v143, 1.0, v143
	v_add_f32_e32 v145, 1.0, v145
	v_rcp_f32_e32 v143, v143
	v_rcp_f32_e32 v145, v145
	v_mul_f32_e32 v84, v84, v143
	v_mul_f32_e32 v85, v85, v145
	v_cvt_pk_bf16_f32 v138, v84, v85
	v_add_u32_e32 v139, 0x41400, v134
	v_add_u32_e32 v140, 0x41400, v135
	global_store_short v139, v138, s[8:9]
	global_store_short_d16_hi v140, v138, s[8:9]
	v_mul_f32_e32 v141, 0xbfb8aa3b, v78
	v_mul_f32_e32 v142, 0xbfb8aa3b, v79
	v_exp_f32_e32 v141, v141
	v_exp_f32_e32 v142, v142
	v_add_f32_e32 v141, 1.0, v141
	v_add_f32_e32 v142, 1.0, v142
	v_rcp_f32_e32 v141, v141
	v_rcp_f32_e32 v142, v142
	v_mul_f32_e32 v78, v78, v141
	v_mul_f32_e32 v79, v79, v142
	v_cvt_pk_bf16_f32 v137, v78, v79
	v_add_u32_e32 v139, 0xae000, v132
	v_add_u32_e32 v140, 0xae000, v133
	global_store_short v139, v137, s[8:9]
	global_store_short_d16_hi v140, v137, s[8:9]
	v_mul_f32_e32 v143, 0xbfb8aa3b, v80
	v_mul_f32_e32 v145, 0xbfb8aa3b, v81
	v_exp_f32_e32 v143, v143
	v_exp_f32_e32 v145, v145
	v_add_f32_e32 v143, 1.0, v143
	v_add_f32_e32 v145, 1.0, v145
	v_rcp_f32_e32 v143, v143
	v_rcp_f32_e32 v145, v145
	v_mul_f32_e32 v80, v80, v143
	v_mul_f32_e32 v81, v81, v145
	v_cvt_pk_bf16_f32 v138, v80, v81
	v_add_u32_e32 v139, 0xae000, v134
	v_add_u32_e32 v140, 0xae000, v135
	global_store_short v139, v138, s[8:9]
	global_store_short_d16_hi v140, v138, s[8:9]
	v_mul_f32_e32 v141, 0xbfb8aa3b, v74
	v_mul_f32_e32 v142, 0xbfb8aa3b, v75
	v_exp_f32_e32 v141, v141
	v_exp_f32_e32 v142, v142
	v_add_f32_e32 v141, 1.0, v141
	v_add_f32_e32 v142, 1.0, v142
	v_rcp_f32_e32 v141, v141
	v_rcp_f32_e32 v142, v142
	v_mul_f32_e32 v74, v74, v141
	v_mul_f32_e32 v75, v75, v142
	v_cvt_pk_bf16_f32 v137, v74, v75
	v_add_u32_e32 v139, 0xc3c00, v132
	v_add_u32_e32 v140, 0xc3c00, v133
	global_store_short v139, v137, s[8:9]
	global_store_short_d16_hi v140, v137, s[8:9]
	v_mul_f32_e32 v143, 0xbfb8aa3b, v76
	v_mul_f32_e32 v145, 0xbfb8aa3b, v77
	v_exp_f32_e32 v143, v143
	v_exp_f32_e32 v145, v145
	v_add_f32_e32 v143, 1.0, v143
	v_add_f32_e32 v145, 1.0, v145
	v_rcp_f32_e32 v143, v143
	v_rcp_f32_e32 v145, v145
	v_mul_f32_e32 v76, v76, v143
	v_mul_f32_e32 v77, v77, v145
	v_cvt_pk_bf16_f32 v138, v76, v77
	v_add_u32_e32 v139, 0xc3c00, v134
	v_add_u32_e32 v140, 0xc3c00, v135
	global_store_short v139, v138, s[8:9]
	global_store_short_d16_hi v140, v138, s[8:9]
	v_mul_f32_e32 v141, 0xbfb8aa3b, v70
	v_mul_f32_e32 v142, 0xbfb8aa3b, v71
	v_exp_f32_e32 v141, v141
	v_exp_f32_e32 v142, v142
	v_add_f32_e32 v141, 1.0, v141
	v_add_f32_e32 v142, 1.0, v142
	v_rcp_f32_e32 v141, v141
	v_rcp_f32_e32 v142, v142
	v_mul_f32_e32 v70, v70, v141
	v_mul_f32_e32 v71, v71, v142
	v_cvt_pk_bf16_f32 v137, v70, v71
	v_add_u32_e32 v139, 0xd9800, v132
	v_add_u32_e32 v140, 0xd9800, v133
	global_store_short v139, v137, s[8:9]
	global_store_short_d16_hi v140, v137, s[8:9]
	v_mul_f32_e32 v143, 0xbfb8aa3b, v72
	v_mul_f32_e32 v145, 0xbfb8aa3b, v73
	v_exp_f32_e32 v143, v143
	v_exp_f32_e32 v145, v145
	v_add_f32_e32 v143, 1.0, v143
	v_add_f32_e32 v145, 1.0, v145
	v_rcp_f32_e32 v143, v143
	v_rcp_f32_e32 v145, v145
	v_mul_f32_e32 v72, v72, v143
	v_mul_f32_e32 v73, v73, v145
	v_cvt_pk_bf16_f32 v138, v72, v73
	v_add_u32_e32 v139, 0xd9800, v134
	v_add_u32_e32 v140, 0xd9800, v135
	global_store_short v139, v138, s[8:9]
	global_store_short_d16_hi v140, v138, s[8:9]
	v_mul_f32_e32 v141, 0xbfb8aa3b, v66
	v_mul_f32_e32 v142, 0xbfb8aa3b, v67
	v_exp_f32_e32 v141, v141
	v_exp_f32_e32 v142, v142
	v_add_f32_e32 v141, 1.0, v141
	v_add_f32_e32 v142, 1.0, v142
	v_rcp_f32_e32 v141, v141
	v_rcp_f32_e32 v142, v142
	v_mul_f32_e32 v66, v66, v141
	v_mul_f32_e32 v67, v67, v142
	v_cvt_pk_bf16_f32 v137, v66, v67
	v_add_u32_e32 v139, 0xef400, v132
	v_add_u32_e32 v140, 0xef400, v133
	global_store_short v139, v137, s[8:9]
	global_store_short_d16_hi v140, v137, s[8:9]
	v_mul_f32_e32 v143, 0xbfb8aa3b, v68
	v_mul_f32_e32 v145, 0xbfb8aa3b, v69
	v_exp_f32_e32 v143, v143
	v_exp_f32_e32 v145, v145
	v_add_f32_e32 v143, 1.0, v143
	v_add_f32_e32 v145, 1.0, v145
	v_rcp_f32_e32 v143, v143
	v_rcp_f32_e32 v145, v145
	v_mul_f32_e32 v68, v68, v143
	v_mul_f32_e32 v69, v69, v145
	v_cvt_pk_bf16_f32 v138, v68, v69
	v_add_u32_e32 v139, 0xef400, v134
	v_add_u32_e32 v140, 0xef400, v135
	global_store_short v139, v138, s[8:9]
	global_store_short_d16_hi v140, v138, s[8:9]
	s_branch .Lipe1_done

; DI u16 f2bf(float x) { unsigned u = __float_as_uint(x); u += 0x7fffu + ((u >> 16) & 1u); return (u16)(u >> 16); }
; DI void phase_inproj(const Params& p, int layer, char* lds) {
;     ...
;           else if (cw >= C_SK && cw < C_SV) { const int o = cw - C_SK; dst = (u16*)(p.ws + OFF_SK) + ((size_t)(bb * 1 * S + (o >> 6) * S) << 6) + (o & 63); dstr = 64; }
;           else if (cw >= C_SV && cw < C_GATE) { const int o = cw - C_SV; dst = (u16*)(p.ws + OFF_SV) + ((size_t)(bb * 1 * S + (o >> 6) * S) << 6) + (o & 63); dstr = 64; }
;         }
;         if (cw < DIN) {
;           float sc = 1.f;
;           if (col >= C_DQ && col < C_DK) sc = SC_DQ;
;           if (col >= C_SQ && col < C_SK) sc = SC_SQ;
;           const bool gate = col >= C_GATE;
; #pragma unroll
;           for (int ai = 0; ai < 2; ++ai)
; #pragma unroll
;             for (int m = 0; m < 4; ++m) {
; #pragma unroll
;               for (int j = 0; j < 4; ++j) {
;                 const int row = m0 + ai * 128 + wr8 * 64 + m * 16 + fq * 4 + j;
;                 float v = acc[ai][bj][m][n][j] * sc;
;                 if (gate) v = v * __builtin_amdgcn_rcpf(1.f + __expf(-v));
;                 dst[(size_t)row * dstr + fr] = f2bf(v);
;               }
;               __builtin_amdgcn_sched_barrier(0);
;             }
;         }
.Lipe1_kv:
	v_cvt_pk_bf16_f32 v137, v94, v95
	global_store_short v136, v137, s[8:9] offset:0
	global_store_short_d16_hi v136, v137, s[8:9] offset:128
	v_cvt_pk_bf16_f32 v138, v96, v97
	global_store_short v136, v138, s[8:9] offset:256
	global_store_short_d16_hi v136, v138, s[8:9] offset:384
	v_add_u32_e32 v139, 0x800, v136
	v_cvt_pk_bf16_f32 v137, v90, v91
	global_store_short v139, v137, s[8:9] offset:0
	global_store_short_d16_hi v139, v137, s[8:9] offset:128
	v_cvt_pk_bf16_f32 v138, v92, v93
	global_store_short v139, v138, s[8:9] offset:256
	global_store_short_d16_hi v139, v138, s[8:9] offset:384
	v_add_u32_e32 v139, 0x1000, v136
	v_cvt_pk_bf16_f32 v137, v86, v87
	global_store_short v139, v137, s[8:9] offset:0
	global_store_short_d16_hi v139, v137, s[8:9] offset:128
	v_cvt_pk_bf16_f32 v138, v88, v89
	global_store_short v139, v138, s[8:9] offset:256
	global_store_short_d16_hi v139, v138, s[8:9] offset:384
	v_add_u32_e32 v139, 0x1800, v136
	v_cvt_pk_bf16_f32 v137, v82, v83
	global_store_short v139, v137, s[8:9] offset:0
	global_store_short_d16_hi v139, v137, s[8:9] offset:128
	v_cvt_pk_bf16_f32 v138, v84, v85
	global_store_short v139, v138, s[8:9] offset:256
	global_store_short_d16_hi v139, v138, s[8:9] offset:384
	v_add_u32_e32 v139, 0x4000, v136
	v_cvt_pk_bf16_f32 v137, v78, v79
	global_store_short v139, v137, s[8:9] offset:0
	global_store_short_d16_hi v139, v137, s[8:9] offset:128
	v_cvt_pk_bf16_f32 v138, v80, v81
	global_store_short v139, v138, s[8:9] offset:256
	global_store_short_d16_hi v139, v138, s[8:9] offset:384
	v_add_u32_e32 v139, 0x4800, v136
	v_cvt_pk_bf16_f32 v137, v74, v75
	global_store_short v139, v137, s[8:9] offset:0
	global_store_short_d16_hi v139, v137, s[8:9] offset:128
	v_cvt_pk_bf16_f32 v138, v76, v77
	global_store_short v139, v138, s[8:9] offset:256
	global_store_short_d16_hi v139, v138, s[8:9] offset:384
	v_add_u32_e32 v139, 0x5000, v136
	v_cvt_pk_bf16_f32 v137, v70, v71
	global_store_short v139, v137, s[8:9] offset:0
	global_store_short_d16_hi v139, v137, s[8:9] offset:128
	v_cvt_pk_bf16_f32 v138, v72, v73
	global_store_short v139, v138, s[8:9] offset:256
	global_store_short_d16_hi v139, v138, s[8:9] offset:384
	v_add_u32_e32 v139, 0x5800, v136
	v_cvt_pk_bf16_f32 v137, v66, v67
	global_store_short v139, v137, s[8:9] offset:0
	global_store_short_d16_hi v139, v137, s[8:9] offset:128
	v_cvt_pk_bf16_f32 v138, v68, v69
	global_store_short v139, v138, s[8:9] offset:256
	global_store_short_d16_hi v139, v138, s[8:9] offset:384
.Lipe1_done:
	s_add_u32 s25, s6, s26
	s_add_u32 s25, s25, 128
	s_cmpk_ge_u32 s25, 2784
	s_cbranch_scc1 .Lipe2_done
	s_cmpk_ge_u32 s25, 1760
	s_cbranch_scc1 .Lipe2_gate
	s_cmpk_ge_u32 s25, 1632
	s_cbranch_scc1 .Lipe2_sv
	s_cmpk_ge_u32 s25, 1504
	s_cbranch_scc1 .Lipe2_sk
	s_cmpk_ge_u32 s25, 1120
	s_cbranch_scc1 .Lipe2_sq
	s_cmpk_ge_u32 s25, 864
	s_cbranch_scc1 .Lipe2_dv
	s_cmpk_ge_u32 s25, 608
	s_cbranch_scc1 .Lipe2_dk
	s_cmpk_ge_u32 s25, 352
	s_cbranch_scc1 .Lipe2_dq
	s_mul_i32 s10, s4, 0x15c0
	s_lshl_b32 s11, s25, 1
	s_add_u32 s10, s10, s11
	s_add_u32 s8, s50, s10
	s_addc_u32 s9, s51, 0
	v_cvt_pk_bf16_f32 v137, v62, v63
	global_store_short v132, v137, s[8:9]
	global_store_short_d16_hi v133, v137, s[8:9]
	v_cvt_pk_bf16_f32 v138, v64, v65
	global_store_short v134, v138, s[8:9]
	global_store_short_d16_hi v135, v138, s[8:9]
	v_cvt_pk_bf16_f32 v137, v58, v59
	v_add_u32_e32 v139, 0x15c00, v132
	v_add_u32_e32 v140, 0x15c00, v133
	global_store_short v139, v137, s[8:9]
	global_store_short_d16_hi v140, v137, s[8:9]
	v_cvt_pk_bf16_f32 v138, v60, v61
	v_add_u32_e32 v139, 0x15c00, v134
	v_add_u32_e32 v140, 0x15c00, v135
	global_store_short v139, v138, s[8:9]
	global_store_short_d16_hi v140, v138, s[8:9]
	v_cvt_pk_bf16_f32 v137, v54, v55
	v_add_u32_e32 v139, 0x2b800, v132
	v_add_u32_e32 v140, 0x2b800, v133
	global_store_short v139, v137, s[8:9]
	global_store_short_d16_hi v140, v137, s[8:9]
	v_cvt_pk_bf16_f32 v138, v56, v57
	v_add_u32_e32 v139, 0x2b800, v134
	v_add_u32_e32 v140, 0x2b800, v135
	global_store_short v139, v138, s[8:9]
	global_store_short_d16_hi v140, v138, s[8:9]
	v_cvt_pk_bf16_f32 v137, v50, v51
	v_add_u32_e32 v139, 0x41400, v132
	v_add_u32_e32 v140, 0x41400, v133
	global_store_short v139, v137, s[8:9]
	global_store_short_d16_hi v140, v137, s[8:9]
	v_cvt_pk_bf16_f32 v138, v52, v53
	v_add_u32_e32 v139, 0x41400, v134
	v_add_u32_e32 v140, 0x41400, v135
	global_store_short v139, v138, s[8:9]
	global_store_short_d16_hi v140, v138, s[8:9]
	v_cvt_pk_bf16_f32 v137, v46, v47
	v_add_u32_e32 v139, 0xae000, v132
	v_add_u32_e32 v140, 0xae000, v133
	global_store_short v139, v137, s[8:9]
	global_store_short_d16_hi v140, v137, s[8:9]
	v_cvt_pk_bf16_f32 v138, v48, v49
	v_add_u32_e32 v139, 0xae000, v134
	v_add_u32_e32 v140, 0xae000, v135
	global_store_short v139, v138, s[8:9]
	global_store_short_d16_hi v140, v138, s[8:9]
	v_cvt_pk_bf16_f32 v137, v42, v43
	v_add_u32_e32 v139, 0xc3c00, v132
	v_add_u32_e32 v140, 0xc3c00, v133
	global_store_short v139, v137, s[8:9]
	global_store_short_d16_hi v140, v137, s[8:9]
	v_cvt_pk_bf16_f32 v138, v44, v45
	v_add_u32_e32 v139, 0xc3c00, v134
	v_add_u32_e32 v140, 0xc3c00, v135
	global_store_short v139, v138, s[8:9]
	global_store_short_d16_hi v140, v138, s[8:9]
	v_cvt_pk_bf16_f32 v137, v38, v39
	v_add_u32_e32 v139, 0xd9800, v132
	v_add_u32_e32 v140, 0xd9800, v133
	global_store_short v139, v137, s[8:9]
	global_store_short_d16_hi v140, v137, s[8:9]
	v_cvt_pk_bf16_f32 v138, v40, v41
	v_add_u32_e32 v139, 0xd9800, v134
	v_add_u32_e32 v140, 0xd9800, v135
	global_store_short v139, v138, s[8:9]
	global_store_short_d16_hi v140, v138, s[8:9]
	v_cvt_pk_bf16_f32 v137, v34, v35
	v_add_u32_e32 v139, 0xef400, v132
	v_add_u32_e32 v140, 0xef400, v133
	global_store_short v139, v137, s[8:9]
	global_store_short_d16_hi v140, v137, s[8:9]
	v_cvt_pk_bf16_f32 v138, v36, v37
	v_add_u32_e32 v139, 0xef400, v134
	v_add_u32_e32 v140, 0xef400, v135
	global_store_short v139, v138, s[8:9]
	global_store_short_d16_hi v140, v138, s[8:9]
	s_branch .Lipe2_done

; DI u16 f2bf(float x) { unsigned u = __float_as_uint(x); u += 0x7fffu + ((u >> 16) & 1u); return (u16)(u >> 16); }
; DI void phase_inproj(const Params& p, int layer, char* lds) {
;     ...
;         if (cw < DIN) {
;           float sc = 1.f;
;           if (col >= C_DQ && col < C_DK) sc = SC_DQ;
;           if (col >= C_SQ && col < C_SK) sc = SC_SQ;
;           const bool gate = col >= C_GATE;
; #pragma unroll
;           for (int ai = 0; ai < 2; ++ai)
; #pragma unroll
;             for (int m = 0; m < 4; ++m) {
; #pragma unroll
;               for (int j = 0; j < 4; ++j) {
;                 const int row = m0 + ai * 128 + wr8 * 64 + m * 16 + fq * 4 + j;
;                 float v = acc[ai][bj][m][n][j] * sc;
;                 if (gate) v = v * __builtin_amdgcn_rcpf(1.f + __expf(-v));
;                 dst[(size_t)row * dstr + fr] = f2bf(v);
;               }
.Lipe2_scaled:
	s_mul_i32 s10, s4, 0x15c0
	s_lshl_b32 s11, s25, 1
	s_add_u32 s10, s10, s11
	s_add_u32 s8, s50, s10
	s_addc_u32 s9, s51, 0
	v_mul_f32_e32 v62, v146, v62
	v_mul_f32_e32 v63, v146, v63
	v_cvt_pk_bf16_f32 v137, v62, v63
	global_store_short v132, v137, s[8:9]
	global_store_short_d16_hi v133, v137, s[8:9]
	v_mul_f32_e32 v64, v146, v64
	v_mul_f32_e32 v65, v146, v65
	v_cvt_pk_bf16_f32 v138, v64, v65
	global_store_short v134, v138, s[8:9]
	global_store_short_d16_hi v135, v138, s[8:9]
	v_mul_f32_e32 v58, v146, v58
	v_mul_f32_e32 v59, v146, v59
	v_cvt_pk_bf16_f32 v137, v58, v59
	v_add_u32_e32 v139, 0x15c00, v132
	v_add_u32_e32 v140, 0x15c00, v133
	global_store_short v139, v137, s[8:9]
	global_store_short_d16_hi v140, v137, s[8:9]
	v_mul_f32_e32 v60, v146, v60
	v_mul_f32_e32 v61, v146, v61
	v_cvt_pk_bf16_f32 v138, v60, v61
	v_add_u32_e32 v139, 0x15c00, v134
	v_add_u32_e32 v140, 0x15c00, v135
	global_store_short v139, v138, s[8:9]
	global_store_short_d16_hi v140, v138, s[8:9]
	v_mul_f32_e32 v54, v146, v54
	v_mul_f32_e32 v55, v146, v55
	v_cvt_pk_bf16_f32 v137, v54, v55
	v_add_u32_e32 v139, 0x2b800, v132
	v_add_u32_e32 v140, 0x2b800, v133
	global_store_short v139, v137, s[8:9]
	global_store_short_d16_hi v140, v137, s[8:9]
	v_mul_f32_e32 v56, v146, v56
	v_mul_f32_e32 v57, v146, v57
	v_cvt_pk_bf16_f32 v138, v56, v57
	v_add_u32_e32 v139, 0x2b800, v134
	v_add_u32_e32 v140, 0x2b800, v135
	global_store_short v139, v138, s[8:9]
	global_store_short_d16_hi v140, v138, s[8:9]
	v_mul_f32_e32 v50, v146, v50
	v_mul_f32_e32 v51, v146, v51
	v_cvt_pk_bf16_f32 v137, v50, v51
	v_add_u32_e32 v139, 0x41400, v132
	v_add_u32_e32 v140, 0x41400, v133
	global_store_short v139, v137, s[8:9]
	global_store_short_d16_hi v140, v137, s[8:9]
	v_mul_f32_e32 v52, v146, v52
	v_mul_f32_e32 v53, v146, v53
	v_cvt_pk_bf16_f32 v138, v52, v53
	v_add_u32_e32 v139, 0x41400, v134
	v_add_u32_e32 v140, 0x41400, v135
	global_store_short v139, v138, s[8:9]
	global_store_short_d16_hi v140, v138, s[8:9]
	v_mul_f32_e32 v46, v146, v46
	v_mul_f32_e32 v47, v146, v47
	v_cvt_pk_bf16_f32 v137, v46, v47
	v_add_u32_e32 v139, 0xae000, v132
	v_add_u32_e32 v140, 0xae000, v133
	global_store_short v139, v137, s[8:9]
	global_store_short_d16_hi v140, v137, s[8:9]
	v_mul_f32_e32 v48, v146, v48
	v_mul_f32_e32 v49, v146, v49
	v_cvt_pk_bf16_f32 v138, v48, v49
	v_add_u32_e32 v139, 0xae000, v134
	v_add_u32_e32 v140, 0xae000, v135
	global_store_short v139, v138, s[8:9]
	global_store_short_d16_hi v140, v138, s[8:9]
	v_mul_f32_e32 v42, v146, v42
	v_mul_f32_e32 v43, v146, v43
	v_cvt_pk_bf16_f32 v137, v42, v43
	v_add_u32_e32 v139, 0xc3c00, v132
	v_add_u32_e32 v140, 0xc3c00, v133
	global_store_short v139, v137, s[8:9]
	global_store_short_d16_hi v140, v137, s[8:9]
	v_mul_f32_e32 v44, v146, v44
	v_mul_f32_e32 v45, v146, v45
	v_cvt_pk_bf16_f32 v138, v44, v45
	v_add_u32_e32 v139, 0xc3c00, v134
	v_add_u32_e32 v140, 0xc3c00, v135
	global_store_short v139, v138, s[8:9]
	global_store_short_d16_hi v140, v138, s[8:9]
	v_mul_f32_e32 v38, v146, v38
	v_mul_f32_e32 v39, v146, v39
	v_cvt_pk_bf16_f32 v137, v38, v39
	v_add_u32_e32 v139, 0xd9800, v132
	v_add_u32_e32 v140, 0xd9800, v133
	global_store_short v139, v137, s[8:9]
	global_store_short_d16_hi v140, v137, s[8:9]
	v_mul_f32_e32 v40, v146, v40
	v_mul_f32_e32 v41, v146, v41
	v_cvt_pk_bf16_f32 v138, v40, v41
	v_add_u32_e32 v139, 0xd9800, v134
	v_add_u32_e32 v140, 0xd9800, v135
	global_store_short v139, v138, s[8:9]
	global_store_short_d16_hi v140, v138, s[8:9]
	v_mul_f32_e32 v34, v146, v34
	v_mul_f32_e32 v35, v146, v35
	v_cvt_pk_bf16_f32 v137, v34, v35
	v_add_u32_e32 v139, 0xef400, v132
	v_add_u32_e32 v140, 0xef400, v133
	global_store_short v139, v137, s[8:9]
	global_store_short_d16_hi v140, v137, s[8:9]
	v_mul_f32_e32 v36, v146, v36
	v_mul_f32_e32 v37, v146, v37
	v_cvt_pk_bf16_f32 v138, v36, v37
	v_add_u32_e32 v139, 0xef400, v134
	v_add_u32_e32 v140, 0xef400, v135
	global_store_short v139, v138, s[8:9]
	global_store_short_d16_hi v140, v138, s[8:9]
	s_branch .Lipe2_done
.Lipe2_gate:
	s_mul_i32 s10, s4, 0x15c0
	s_lshl_b32 s11, s25, 1
	s_add_u32 s10, s10, s11
	s_add_u32 s8, s50, s10
	s_addc_u32 s9, s51, 0
	v_mul_f32_e32 v141, 0xbfb8aa3b, v62
	v_mul_f32_e32 v142, 0xbfb8aa3b, v63
	v_exp_f32_e32 v141, v141
	v_exp_f32_e32 v142, v142
	v_add_f32_e32 v141, 1.0, v141
	v_add_f32_e32 v142, 1.0, v142
	v_rcp_f32_e32 v141, v141
	v_rcp_f32_e32 v142, v142
	v_mul_f32_e32 v62, v62, v141
	v_mul_f32_e32 v63, v63, v142
	v_cvt_pk_bf16_f32 v137, v62, v63
	global_store_short v132, v137, s[8:9]
	global_store_short_d16_hi v133, v137, s[8:9]
	v_mul_f32_e32 v143, 0xbfb8aa3b, v64
	v_mul_f32_e32 v145, 0xbfb8aa3b, v65
	v_exp_f32_e32 v143, v143
	v_exp_f32_e32 v145, v145
	v_add_f32_e32 v143, 1.0, v143
	v_add_f32_e32 v145, 1.0, v145
	v_rcp_f32_e32 v143, v143
	v_rcp_f32_e32 v145, v145
	v_mul_f32_e32 v64, v64, v143
	v_mul_f32_e32 v65, v65, v145
	v_cvt_pk_bf16_f32 v138, v64, v65
	global_store_short v134, v138, s[8:9]
	global_store_short_d16_hi v135, v138, s[8:9]
	v_mul_f32_e32 v141, 0xbfb8aa3b, v58
	v_mul_f32_e32 v142, 0xbfb8aa3b, v59
	v_exp_f32_e32 v141, v141
	v_exp_f32_e32 v142, v142
	v_add_f32_e32 v141, 1.0, v141
	v_add_f32_e32 v142, 1.0, v142
	v_rcp_f32_e32 v141, v141
	v_rcp_f32_e32 v142, v142
	v_mul_f32_e32 v58, v58, v141
	v_mul_f32_e32 v59, v59, v142
	v_cvt_pk_bf16_f32 v137, v58, v59
	v_add_u32_e32 v139, 0x15c00, v132
	v_add_u32_e32 v140, 0x15c00, v133
	global_store_short v139, v137, s[8:9]
	global_store_short_d16_hi v140, v137, s[8:9]
	v_mul_f32_e32 v143, 0xbfb8aa3b, v60
	v_mul_f32_e32 v145, 0xbfb8aa3b, v61
	v_exp_f32_e32 v143, v143
	v_exp_f32_e32 v145, v145
	v_add_f32_e32 v143, 1.0, v143
	v_add_f32_e32 v145, 1.0, v145
; DI u16 f2bf(float x) { unsigned u = __float_as_uint(x); u += 0x7fffu + ((u >> 16) & 1u); return (u16)(u >> 16); }
; DI void phase_inproj(const Params& p, int layer, char* lds) {
;     ...
;         if (cw < DIN) {
;           float sc = 1.f;
;           if (col >= C_DQ && col < C_DK) sc = SC_DQ;
;           if (col >= C_SQ && col < C_SK) sc = SC_SQ;
;           const bool gate = col >= C_GATE;
; #pragma unroll
;           for (int ai = 0; ai < 2; ++ai)
; #pragma unroll
;             for (int m = 0; m < 4; ++m) {
; #pragma unroll
;               for (int j = 0; j < 4; ++j) {
;                 const int row = m0 + ai * 128 + wr8 * 64 + m * 16 + fq * 4 + j;
;                 float v = acc[ai][bj][m][n][j] * sc;
;                 if (gate) v = v * __builtin_amdgcn_rcpf(1.f + __expf(-v));
;                 dst[(size_t)row * dstr + fr] = f2bf(v);
;               }
	v_rcp_f32_e32 v143, v143
	v_rcp_f32_e32 v145, v145
	v_mul_f32_e32 v60, v60, v143
	v_mul_f32_e32 v61, v61, v145
	v_cvt_pk_bf16_f32 v138, v60, v61
	v_add_u32_e32 v139, 0x15c00, v134
	v_add_u32_e32 v140, 0x15c00, v135
	global_store_short v139, v138, s[8:9]
	global_store_short_d16_hi v140, v138, s[8:9]
	v_mul_f32_e32 v141, 0xbfb8aa3b, v54
	v_mul_f32_e32 v142, 0xbfb8aa3b, v55
	v_exp_f32_e32 v141, v141
	v_exp_f32_e32 v142, v142
	v_add_f32_e32 v141, 1.0, v141
	v_add_f32_e32 v142, 1.0, v142
	v_rcp_f32_e32 v141, v141
	v_rcp_f32_e32 v142, v142
	v_mul_f32_e32 v54, v54, v141
	v_mul_f32_e32 v55, v55, v142
	v_cvt_pk_bf16_f32 v137, v54, v55
	v_add_u32_e32 v139, 0x2b800, v132
	v_add_u32_e32 v140, 0x2b800, v133
	global_store_short v139, v137, s[8:9]
	global_store_short_d16_hi v140, v137, s[8:9]
	v_mul_f32_e32 v143, 0xbfb8aa3b, v56
	v_mul_f32_e32 v145, 0xbfb8aa3b, v57
	v_exp_f32_e32 v143, v143
	v_exp_f32_e32 v145, v145
	v_add_f32_e32 v143, 1.0, v143
	v_add_f32_e32 v145, 1.0, v145
	v_rcp_f32_e32 v143, v143
	v_rcp_f32_e32 v145, v145
	v_mul_f32_e32 v56, v56, v143
	v_mul_f32_e32 v57, v57, v145
	v_cvt_pk_bf16_f32 v138, v56, v57
	v_add_u32_e32 v139, 0x2b800, v134
	v_add_u32_e32 v140, 0x2b800, v135
	global_store_short v139, v138, s[8:9]
	global_store_short_d16_hi v140, v138, s[8:9]
	v_mul_f32_e32 v141, 0xbfb8aa3b, v50
	v_mul_f32_e32 v142, 0xbfb8aa3b, v51
	v_exp_f32_e32 v141, v141
	v_exp_f32_e32 v142, v142
	v_add_f32_e32 v141, 1.0, v141
	v_add_f32_e32 v142, 1.0, v142
	v_rcp_f32_e32 v141, v141
	v_rcp_f32_e32 v142, v142
	v_mul_f32_e32 v50, v50, v141
	v_mul_f32_e32 v51, v51, v142
	v_cvt_pk_bf16_f32 v137, v50, v51
	v_add_u32_e32 v139, 0x41400, v132
	v_add_u32_e32 v140, 0x41400, v133
	global_store_short v139, v137, s[8:9]
	global_store_short_d16_hi v140, v137, s[8:9]
	v_mul_f32_e32 v143, 0xbfb8aa3b, v52
	v_mul_f32_e32 v145, 0xbfb8aa3b, v53
	v_exp_f32_e32 v143, v143
	v_exp_f32_e32 v145, v145
	v_add_f32_e32 v143, 1.0, v143
	v_add_f32_e32 v145, 1.0, v145
	v_rcp_f32_e32 v143, v143
	v_rcp_f32_e32 v145, v145
	v_mul_f32_e32 v52, v52, v143
	v_mul_f32_e32 v53, v53, v145
	v_cvt_pk_bf16_f32 v138, v52, v53
	v_add_u32_e32 v139, 0x41400, v134
	v_add_u32_e32 v140, 0x41400, v135
	global_store_short v139, v138, s[8:9]
	global_store_short_d16_hi v140, v138, s[8:9]
	v_mul_f32_e32 v141, 0xbfb8aa3b, v46
	v_mul_f32_e32 v142, 0xbfb8aa3b, v47
	v_exp_f32_e32 v141, v141
	v_exp_f32_e32 v142, v142
	v_add_f32_e32 v141, 1.0, v141
	v_add_f32_e32 v142, 1.0, v142
	v_rcp_f32_e32 v141, v141
	v_rcp_f32_e32 v142, v142
	v_mul_f32_e32 v46, v46, v141
	v_mul_f32_e32 v47, v47, v142
	v_cvt_pk_bf16_f32 v137, v46, v47
	v_add_u32_e32 v139, 0xae000, v132
	v_add_u32_e32 v140, 0xae000, v133
	global_store_short v139, v137, s[8:9]
	global_store_short_d16_hi v140, v137, s[8:9]
	v_mul_f32_e32 v143, 0xbfb8aa3b, v48
	v_mul_f32_e32 v145, 0xbfb8aa3b, v49
	v_exp_f32_e32 v143, v143
	v_exp_f32_e32 v145, v145
	v_add_f32_e32 v143, 1.0, v143
	v_add_f32_e32 v145, 1.0, v145
	v_rcp_f32_e32 v143, v143
	v_rcp_f32_e32 v145, v145
	v_mul_f32_e32 v48, v48, v143
	v_mul_f32_e32 v49, v49, v145
	v_cvt_pk_bf16_f32 v138, v48, v49
	v_add_u32_e32 v139, 0xae000, v134
	v_add_u32_e32 v140, 0xae000, v135
	global_store_short v139, v138, s[8:9]
	global_store_short_d16_hi v140, v138, s[8:9]
	v_mul_f32_e32 v141, 0xbfb8aa3b, v42
	v_mul_f32_e32 v142, 0xbfb8aa3b, v43
	v_exp_f32_e32 v141, v141
	v_exp_f32_e32 v142, v142
	v_add_f32_e32 v141, 1.0, v141
	v_add_f32_e32 v142, 1.0, v142
	v_rcp_f32_e32 v141, v141
	v_rcp_f32_e32 v142, v142
	v_mul_f32_e32 v42, v42, v141
	v_mul_f32_e32 v43, v43, v142
	v_cvt_pk_bf16_f32 v137, v42, v43
	v_add_u32_e32 v139, 0xc3c00, v132
	v_add_u32_e32 v140, 0xc3c00, v133
	global_store_short v139, v137, s[8:9]
	global_store_short_d16_hi v140, v137, s[8:9]
	v_mul_f32_e32 v143, 0xbfb8aa3b, v44
	v_mul_f32_e32 v145, 0xbfb8aa3b, v45
	v_exp_f32_e32 v143, v143
	v_exp_f32_e32 v145, v145
	v_add_f32_e32 v143, 1.0, v143
	v_add_f32_e32 v145, 1.0, v145
	v_rcp_f32_e32 v143, v143
	v_rcp_f32_e32 v145, v145
	v_mul_f32_e32 v44, v44, v143
	v_mul_f32_e32 v45, v45, v145
	v_cvt_pk_bf16_f32 v138, v44, v45
	v_add_u32_e32 v139, 0xc3c00, v134
	v_add_u32_e32 v140, 0xc3c00, v135
	global_store_short v139, v138, s[8:9]
	global_store_short_d16_hi v140, v138, s[8:9]
	v_mul_f32_e32 v141, 0xbfb8aa3b, v38
	v_mul_f32_e32 v142, 0xbfb8aa3b, v39
	v_exp_f32_e32 v141, v141
	v_exp_f32_e32 v142, v142
	v_add_f32_e32 v141, 1.0, v141
	v_add_f32_e32 v142, 1.0, v142
	v_rcp_f32_e32 v141, v141
	v_rcp_f32_e32 v142, v142
	v_mul_f32_e32 v38, v38, v141
	v_mul_f32_e32 v39, v39, v142
	v_cvt_pk_bf16_f32 v137, v38, v39
	v_add_u32_e32 v139, 0xd9800, v132
	v_add_u32_e32 v140, 0xd9800, v133
	global_store_short v139, v137, s[8:9]
	global_store_short_d16_hi v140, v137, s[8:9]
	v_mul_f32_e32 v143, 0xbfb8aa3b, v40
	v_mul_f32_e32 v145, 0xbfb8aa3b, v41
	v_exp_f32_e32 v143, v143
	v_exp_f32_e32 v145, v145
	v_add_f32_e32 v143, 1.0, v143
	v_add_f32_e32 v145, 1.0, v145
	v_rcp_f32_e32 v143, v143
	v_rcp_f32_e32 v145, v145
	v_mul_f32_e32 v40, v40, v143
	v_mul_f32_e32 v41, v41, v145
	v_cvt_pk_bf16_f32 v138, v40, v41
	v_add_u32_e32 v139, 0xd9800, v134
	v_add_u32_e32 v140, 0xd9800, v135
	global_store_short v139, v138, s[8:9]
	global_store_short_d16_hi v140, v138, s[8:9]
	v_mul_f32_e32 v141, 0xbfb8aa3b, v34
	v_mul_f32_e32 v142, 0xbfb8aa3b, v35
	v_exp_f32_e32 v141, v141
	v_exp_f32_e32 v142, v142
	v_add_f32_e32 v141, 1.0, v141
	v_add_f32_e32 v142, 1.0, v142
	v_rcp_f32_e32 v141, v141
	v_rcp_f32_e32 v142, v142
	v_mul_f32_e32 v34, v34, v141
	v_mul_f32_e32 v35, v35, v142
	v_cvt_pk_bf16_f32 v137, v34, v35
	v_add_u32_e32 v139, 0xef400, v132
	v_add_u32_e32 v140, 0xef400, v133
	global_store_short v139, v137, s[8:9]
	global_store_short_d16_hi v140, v137, s[8:9]
	v_mul_f32_e32 v143, 0xbfb8aa3b, v36
	v_mul_f32_e32 v145, 0xbfb8aa3b, v37
	v_exp_f32_e32 v143, v143
	v_exp_f32_e32 v145, v145
	v_add_f32_e32 v143, 1.0, v143
	v_add_f32_e32 v145, 1.0, v145
	v_rcp_f32_e32 v143, v143
	v_rcp_f32_e32 v145, v145
	v_mul_f32_e32 v36, v36, v143
	v_mul_f32_e32 v37, v37, v145
	v_cvt_pk_bf16_f32 v138, v36, v37
	v_add_u32_e32 v139, 0xef400, v134
	v_add_u32_e32 v140, 0xef400, v135
	global_store_short v139, v138, s[8:9]
	global_store_short_d16_hi v140, v138, s[8:9]
	s_branch .Lipe2_done

; DI u16 f2bf(float x) { unsigned u = __float_as_uint(x); u += 0x7fffu + ((u >> 16) & 1u); return (u16)(u >> 16); }
; DI void phase_inproj(const Params& p, int layer, char* lds) {
;     ...
;           else if (cw >= C_SK && cw < C_SV) { const int o = cw - C_SK; dst = (u16*)(p.ws + OFF_SK) + ((size_t)(bb * 1 * S + (o >> 6) * S) << 6) + (o & 63); dstr = 64; }
;           else if (cw >= C_SV && cw < C_GATE) { const int o = cw - C_SV; dst = (u16*)(p.ws + OFF_SV) + ((size_t)(bb * 1 * S + (o >> 6) * S) << 6) + (o & 63); dstr = 64; }
;         }
;         if (cw < DIN) {
;           float sc = 1.f;
;           if (col >= C_DQ && col < C_DK) sc = SC_DQ;
;           if (col >= C_SQ && col < C_SK) sc = SC_SQ;
;           const bool gate = col >= C_GATE;
; #pragma unroll
;           for (int ai = 0; ai < 2; ++ai)
; #pragma unroll
;             for (int m = 0; m < 4; ++m) {
; #pragma unroll
;               for (int j = 0; j < 4; ++j) {
;                 const int row = m0 + ai * 128 + wr8 * 64 + m * 16 + fq * 4 + j;
;                 float v = acc[ai][bj][m][n][j] * sc;
;                 if (gate) v = v * __builtin_amdgcn_rcpf(1.f + __expf(-v));
;                 dst[(size_t)row * dstr + fr] = f2bf(v);
;               }
;               __builtin_amdgcn_sched_barrier(0);
;             }
;         }
.Lipe2_kv:
	v_cvt_pk_bf16_f32 v137, v62, v63
	global_store_short v136, v137, s[8:9] offset:0
	global_store_short_d16_hi v136, v137, s[8:9] offset:128
	v_cvt_pk_bf16_f32 v138, v64, v65
	global_store_short v136, v138, s[8:9] offset:256
	global_store_short_d16_hi v136, v138, s[8:9] offset:384
	v_add_u32_e32 v139, 0x800, v136
	v_cvt_pk_bf16_f32 v137, v58, v59
	global_store_short v139, v137, s[8:9] offset:0
	global_store_short_d16_hi v139, v137, s[8:9] offset:128
	v_cvt_pk_bf16_f32 v138, v60, v61
	global_store_short v139, v138, s[8:9] offset:256
	global_store_short_d16_hi v139, v138, s[8:9] offset:384
	v_add_u32_e32 v139, 0x1000, v136
	v_cvt_pk_bf16_f32 v137, v54, v55
	global_store_short v139, v137, s[8:9] offset:0
	global_store_short_d16_hi v139, v137, s[8:9] offset:128
	v_cvt_pk_bf16_f32 v138, v56, v57
	global_store_short v139, v138, s[8:9] offset:256
	global_store_short_d16_hi v139, v138, s[8:9] offset:384
	v_add_u32_e32 v139, 0x1800, v136
	v_cvt_pk_bf16_f32 v137, v50, v51
	global_store_short v139, v137, s[8:9] offset:0
	global_store_short_d16_hi v139, v137, s[8:9] offset:128
	v_cvt_pk_bf16_f32 v138, v52, v53
	global_store_short v139, v138, s[8:9] offset:256
	global_store_short_d16_hi v139, v138, s[8:9] offset:384
	v_add_u32_e32 v139, 0x4000, v136
	v_cvt_pk_bf16_f32 v137, v46, v47
	global_store_short v139, v137, s[8:9] offset:0
	global_store_short_d16_hi v139, v137, s[8:9] offset:128
	v_cvt_pk_bf16_f32 v138, v48, v49
	global_store_short v139, v138, s[8:9] offset:256
	global_store_short_d16_hi v139, v138, s[8:9] offset:384
	v_add_u32_e32 v139, 0x4800, v136
	v_cvt_pk_bf16_f32 v137, v42, v43
	global_store_short v139, v137, s[8:9] offset:0
	global_store_short_d16_hi v139, v137, s[8:9] offset:128
	v_cvt_pk_bf16_f32 v138, v44, v45
	global_store_short v139, v138, s[8:9] offset:256
	global_store_short_d16_hi v139, v138, s[8:9] offset:384
	v_add_u32_e32 v139, 0x5000, v136
	v_cvt_pk_bf16_f32 v137, v38, v39
	global_store_short v139, v137, s[8:9] offset:0
	global_store_short_d16_hi v139, v137, s[8:9] offset:128
	v_cvt_pk_bf16_f32 v138, v40, v41
	global_store_short v139, v138, s[8:9] offset:256
	global_store_short_d16_hi v139, v138, s[8:9] offset:384
	v_add_u32_e32 v139, 0x5800, v136
	v_cvt_pk_bf16_f32 v137, v34, v35
	global_store_short v139, v137, s[8:9] offset:0
	global_store_short_d16_hi v139, v137, s[8:9] offset:128
	v_cvt_pk_bf16_f32 v138, v36, v37
	global_store_short v139, v138, s[8:9] offset:256
	global_store_short_d16_hi v139, v138, s[8:9] offset:384
.Lipe2_done:
	s_add_u32 s25, s6, s26
	s_add_u32 s25, s25, 144
	s_cmpk_ge_u32 s25, 2784
	s_cbranch_scc1 .Lipe3_done
	s_cmpk_ge_u32 s25, 1760
	s_cbranch_scc1 .Lipe3_gate
	s_cmpk_ge_u32 s25, 1632
	s_cbranch_scc1 .Lipe3_sv
	s_cmpk_ge_u32 s25, 1504
	s_cbranch_scc1 .Lipe3_sk
	s_cmpk_ge_u32 s25, 1120
	s_cbranch_scc1 .Lipe3_sq
	s_cmpk_ge_u32 s25, 864
	s_cbranch_scc1 .Lipe3_dv
	s_cmpk_ge_u32 s25, 608
	s_cbranch_scc1 .Lipe3_dk
	s_cmpk_ge_u32 s25, 352
	s_cbranch_scc1 .Lipe3_dq
	s_mul_i32 s10, s4, 0x15c0
	s_lshl_b32 s11, s25, 1
	s_add_u32 s10, s10, s11
	s_add_u32 s8, s50, s10
	s_addc_u32 s9, s51, 0
	v_cvt_pk_bf16_f32 v137, v30, v31
	global_store_short v132, v137, s[8:9]
	global_store_short_d16_hi v133, v137, s[8:9]
	v_cvt_pk_bf16_f32 v138, v32, v33
	global_store_short v134, v138, s[8:9]
	global_store_short_d16_hi v135, v138, s[8:9]
	v_cvt_pk_bf16_f32 v137, v26, v27
	v_add_u32_e32 v139, 0x15c00, v132
	v_add_u32_e32 v140, 0x15c00, v133
	global_store_short v139, v137, s[8:9]
	global_store_short_d16_hi v140, v137, s[8:9]
	v_cvt_pk_bf16_f32 v138, v28, v29
	v_add_u32_e32 v139, 0x15c00, v134
	v_add_u32_e32 v140, 0x15c00, v135
	global_store_short v139, v138, s[8:9]
	global_store_short_d16_hi v140, v138, s[8:9]
	v_cvt_pk_bf16_f32 v137, v22, v23
	v_add_u32_e32 v139, 0x2b800, v132
	v_add_u32_e32 v140, 0x2b800, v133
	global_store_short v139, v137, s[8:9]
	global_store_short_d16_hi v140, v137, s[8:9]
	v_cvt_pk_bf16_f32 v138, v24, v25
	v_add_u32_e32 v139, 0x2b800, v134
	v_add_u32_e32 v140, 0x2b800, v135
	global_store_short v139, v138, s[8:9]
	global_store_short_d16_hi v140, v138, s[8:9]
	v_cvt_pk_bf16_f32 v137, v18, v19
	v_add_u32_e32 v139, 0x41400, v132
	v_add_u32_e32 v140, 0x41400, v133
	global_store_short v139, v137, s[8:9]
	global_store_short_d16_hi v140, v137, s[8:9]
	v_cvt_pk_bf16_f32 v138, v20, v21
	v_add_u32_e32 v139, 0x41400, v134
	v_add_u32_e32 v140, 0x41400, v135
	global_store_short v139, v138, s[8:9]
	global_store_short_d16_hi v140, v138, s[8:9]
	v_cvt_pk_bf16_f32 v137, v14, v15
	v_add_u32_e32 v139, 0xae000, v132
	v_add_u32_e32 v140, 0xae000, v133
	global_store_short v139, v137, s[8:9]
	global_store_short_d16_hi v140, v137, s[8:9]
	v_cvt_pk_bf16_f32 v138, v16, v17
	v_add_u32_e32 v139, 0xae000, v134
	v_add_u32_e32 v140, 0xae000, v135
	global_store_short v139, v138, s[8:9]
	global_store_short_d16_hi v140, v138, s[8:9]
	v_cvt_pk_bf16_f32 v137, v10, v11
	v_add_u32_e32 v139, 0xc3c00, v132
	v_add_u32_e32 v140, 0xc3c00, v133
	global_store_short v139, v137, s[8:9]
	global_store_short_d16_hi v140, v137, s[8:9]
	v_cvt_pk_bf16_f32 v138, v12, v13
	v_add_u32_e32 v139, 0xc3c00, v134
	v_add_u32_e32 v140, 0xc3c00, v135
	global_store_short v139, v138, s[8:9]
	global_store_short_d16_hi v140, v138, s[8:9]
	v_cvt_pk_bf16_f32 v137, v6, v7
	v_add_u32_e32 v139, 0xd9800, v132
	v_add_u32_e32 v140, 0xd9800, v133
	global_store_short v139, v137, s[8:9]
	global_store_short_d16_hi v140, v137, s[8:9]
	v_cvt_pk_bf16_f32 v138, v8, v9
	v_add_u32_e32 v139, 0xd9800, v134
	v_add_u32_e32 v140, 0xd9800, v135
	global_store_short v139, v138, s[8:9]
	global_store_short_d16_hi v140, v138, s[8:9]
	v_cvt_pk_bf16_f32 v137, v0, v1
	v_add_u32_e32 v139, 0xef400, v132
	v_add_u32_e32 v140, 0xef400, v133
	global_store_short v139, v137, s[8:9]
	global_store_short_d16_hi v140, v137, s[8:9]
	v_cvt_pk_bf16_f32 v138, v2, v3
	v_add_u32_e32 v139, 0xef400, v134
	v_add_u32_e32 v140, 0xef400, v135
	global_store_short v139, v138, s[8:9]
	global_store_short_d16_hi v140, v138, s[8:9]
	s_branch .Lipe3_done

; DI u16 f2bf(float x) { unsigned u = __float_as_uint(x); u += 0x7fffu + ((u >> 16) & 1u); return (u16)(u >> 16); }
; DI void phase_inproj(const Params& p, int layer, char* lds) {
;     ...
;         if (cw < DIN) {
;           float sc = 1.f;
;           if (col >= C_DQ && col < C_DK) sc = SC_DQ;
;           if (col >= C_SQ && col < C_SK) sc = SC_SQ;
;           const bool gate = col >= C_GATE;
; #pragma unroll
;           for (int ai = 0; ai < 2; ++ai)
; #pragma unroll
;             for (int m = 0; m < 4; ++m) {
; #pragma unroll
;               for (int j = 0; j < 4; ++j) {
;                 const int row = m0 + ai * 128 + wr8 * 64 + m * 16 + fq * 4 + j;
;                 float v = acc[ai][bj][m][n][j] * sc;
;                 if (gate) v = v * __builtin_amdgcn_rcpf(1.f + __expf(-v));
;                 dst[(size_t)row * dstr + fr] = f2bf(v);
;               }
.Lipe3_scaled:
	s_mul_i32 s10, s4, 0x15c0
	s_lshl_b32 s11, s25, 1
	s_add_u32 s10, s10, s11
	s_add_u32 s8, s50, s10
	s_addc_u32 s9, s51, 0
	v_mul_f32_e32 v30, v146, v30
	v_mul_f32_e32 v31, v146, v31
	v_cvt_pk_bf16_f32 v137, v30, v31
	global_store_short v132, v137, s[8:9]
	global_store_short_d16_hi v133, v137, s[8:9]
	v_mul_f32_e32 v32, v146, v32
	v_mul_f32_e32 v33, v146, v33
	v_cvt_pk_bf16_f32 v138, v32, v33
	global_store_short v134, v138, s[8:9]
	global_store_short_d16_hi v135, v138, s[8:9]
	v_mul_f32_e32 v26, v146, v26
	v_mul_f32_e32 v27, v146, v27
	v_cvt_pk_bf16_f32 v137, v26, v27
	v_add_u32_e32 v139, 0x15c00, v132
	v_add_u32_e32 v140, 0x15c00, v133
	global_store_short v139, v137, s[8:9]
	global_store_short_d16_hi v140, v137, s[8:9]
	v_mul_f32_e32 v28, v146, v28
	v_mul_f32_e32 v29, v146, v29
	v_cvt_pk_bf16_f32 v138, v28, v29
	v_add_u32_e32 v139, 0x15c00, v134
	v_add_u32_e32 v140, 0x15c00, v135
	global_store_short v139, v138, s[8:9]
	global_store_short_d16_hi v140, v138, s[8:9]
	v_mul_f32_e32 v22, v146, v22
	v_mul_f32_e32 v23, v146, v23
	v_cvt_pk_bf16_f32 v137, v22, v23
	v_add_u32_e32 v139, 0x2b800, v132
	v_add_u32_e32 v140, 0x2b800, v133
	global_store_short v139, v137, s[8:9]
	global_store_short_d16_hi v140, v137, s[8:9]
	v_mul_f32_e32 v24, v146, v24
	v_mul_f32_e32 v25, v146, v25
	v_cvt_pk_bf16_f32 v138, v24, v25
	v_add_u32_e32 v139, 0x2b800, v134
	v_add_u32_e32 v140, 0x2b800, v135
	global_store_short v139, v138, s[8:9]
	global_store_short_d16_hi v140, v138, s[8:9]
	v_mul_f32_e32 v18, v146, v18
	v_mul_f32_e32 v19, v146, v19
	v_cvt_pk_bf16_f32 v137, v18, v19
	v_add_u32_e32 v139, 0x41400, v132
	v_add_u32_e32 v140, 0x41400, v133
	global_store_short v139, v137, s[8:9]
	global_store_short_d16_hi v140, v137, s[8:9]
	v_mul_f32_e32 v20, v146, v20
	v_mul_f32_e32 v21, v146, v21
	v_cvt_pk_bf16_f32 v138, v20, v21
	v_add_u32_e32 v139, 0x41400, v134
	v_add_u32_e32 v140, 0x41400, v135
	global_store_short v139, v138, s[8:9]
	global_store_short_d16_hi v140, v138, s[8:9]
	v_mul_f32_e32 v14, v146, v14
	v_mul_f32_e32 v15, v146, v15
	v_cvt_pk_bf16_f32 v137, v14, v15
	v_add_u32_e32 v139, 0xae000, v132
	v_add_u32_e32 v140, 0xae000, v133
	global_store_short v139, v137, s[8:9]
	global_store_short_d16_hi v140, v137, s[8:9]
	v_mul_f32_e32 v16, v146, v16
	v_mul_f32_e32 v17, v146, v17
	v_cvt_pk_bf16_f32 v138, v16, v17
	v_add_u32_e32 v139, 0xae000, v134
	v_add_u32_e32 v140, 0xae000, v135
	global_store_short v139, v138, s[8:9]
	global_store_short_d16_hi v140, v138, s[8:9]
	v_mul_f32_e32 v10, v146, v10
	v_mul_f32_e32 v11, v146, v11
	v_cvt_pk_bf16_f32 v137, v10, v11
	v_add_u32_e32 v139, 0xc3c00, v132
	v_add_u32_e32 v140, 0xc3c00, v133
	global_store_short v139, v137, s[8:9]
	global_store_short_d16_hi v140, v137, s[8:9]
	v_mul_f32_e32 v12, v146, v12
	v_mul_f32_e32 v13, v146, v13
	v_cvt_pk_bf16_f32 v138, v12, v13
	v_add_u32_e32 v139, 0xc3c00, v134
	v_add_u32_e32 v140, 0xc3c00, v135
	global_store_short v139, v138, s[8:9]
	global_store_short_d16_hi v140, v138, s[8:9]
	v_mul_f32_e32 v6, v146, v6
	v_mul_f32_e32 v7, v146, v7
	v_cvt_pk_bf16_f32 v137, v6, v7
	v_add_u32_e32 v139, 0xd9800, v132
	v_add_u32_e32 v140, 0xd9800, v133
	global_store_short v139, v137, s[8:9]
	global_store_short_d16_hi v140, v137, s[8:9]
	v_mul_f32_e32 v8, v146, v8
	v_mul_f32_e32 v9, v146, v9
	v_cvt_pk_bf16_f32 v138, v8, v9
	v_add_u32_e32 v139, 0xd9800, v134
	v_add_u32_e32 v140, 0xd9800, v135
	global_store_short v139, v138, s[8:9]
	global_store_short_d16_hi v140, v138, s[8:9]
	v_mul_f32_e32 v0, v146, v0
	v_mul_f32_e32 v1, v146, v1
	v_cvt_pk_bf16_f32 v137, v0, v1
	v_add_u32_e32 v139, 0xef400, v132
	v_add_u32_e32 v140, 0xef400, v133
	global_store_short v139, v137, s[8:9]
	global_store_short_d16_hi v140, v137, s[8:9]
	v_mul_f32_e32 v2, v146, v2
	v_mul_f32_e32 v3, v146, v3
	v_cvt_pk_bf16_f32 v138, v2, v3
	v_add_u32_e32 v139, 0xef400, v134
	v_add_u32_e32 v140, 0xef400, v135
	global_store_short v139, v138, s[8:9]
	global_store_short_d16_hi v140, v138, s[8:9]
	s_branch .Lipe3_done
.Lipe3_gate:
	s_mul_i32 s10, s4, 0x15c0
	s_lshl_b32 s11, s25, 1
	s_add_u32 s10, s10, s11
	s_add_u32 s8, s50, s10
	s_addc_u32 s9, s51, 0
	v_mul_f32_e32 v141, 0xbfb8aa3b, v30
	v_mul_f32_e32 v142, 0xbfb8aa3b, v31
	v_exp_f32_e32 v141, v141
	v_exp_f32_e32 v142, v142
	v_add_f32_e32 v141, 1.0, v141
	v_add_f32_e32 v142, 1.0, v142
	v_rcp_f32_e32 v141, v141
	v_rcp_f32_e32 v142, v142
	v_mul_f32_e32 v30, v30, v141
	v_mul_f32_e32 v31, v31, v142
	v_cvt_pk_bf16_f32 v137, v30, v31
	global_store_short v132, v137, s[8:9]
	global_store_short_d16_hi v133, v137, s[8:9]
	v_mul_f32_e32 v143, 0xbfb8aa3b, v32
	v_mul_f32_e32 v145, 0xbfb8aa3b, v33
	v_exp_f32_e32 v143, v143
	v_exp_f32_e32 v145, v145
	v_add_f32_e32 v143, 1.0, v143
	v_add_f32_e32 v145, 1.0, v145
	v_rcp_f32_e32 v143, v143
	v_rcp_f32_e32 v145, v145
	v_mul_f32_e32 v32, v32, v143
	v_mul_f32_e32 v33, v33, v145
	v_cvt_pk_bf16_f32 v138, v32, v33
	global_store_short v134, v138, s[8:9]
	global_store_short_d16_hi v135, v138, s[8:9]
	v_mul_f32_e32 v141, 0xbfb8aa3b, v26
	v_mul_f32_e32 v142, 0xbfb8aa3b, v27
	v_exp_f32_e32 v141, v141
	v_exp_f32_e32 v142, v142
	v_add_f32_e32 v141, 1.0, v141
	v_add_f32_e32 v142, 1.0, v142
	v_rcp_f32_e32 v141, v141
	v_rcp_f32_e32 v142, v142
	v_mul_f32_e32 v26, v26, v141
	v_mul_f32_e32 v27, v27, v142
	v_cvt_pk_bf16_f32 v137, v26, v27
	v_add_u32_e32 v139, 0x15c00, v132
	v_add_u32_e32 v140, 0x15c00, v133
	global_store_short v139, v137, s[8:9]
	global_store_short_d16_hi v140, v137, s[8:9]
	v_mul_f32_e32 v143, 0xbfb8aa3b, v28
	v_mul_f32_e32 v145, 0xbfb8aa3b, v29
	v_exp_f32_e32 v143, v143
	v_exp_f32_e32 v145, v145
	v_add_f32_e32 v143, 1.0, v143
	v_add_f32_e32 v145, 1.0, v145
; DI u16 f2bf(float x) { unsigned u = __float_as_uint(x); u += 0x7fffu + ((u >> 16) & 1u); return (u16)(u >> 16); }
; DI void phase_inproj(const Params& p, int layer, char* lds) {
;     ...
;         if (cw < DIN) {
;           float sc = 1.f;
;           if (col >= C_DQ && col < C_DK) sc = SC_DQ;
;           if (col >= C_SQ && col < C_SK) sc = SC_SQ;
;           const bool gate = col >= C_GATE;
; #pragma unroll
;           for (int ai = 0; ai < 2; ++ai)
; #pragma unroll
;             for (int m = 0; m < 4; ++m) {
; #pragma unroll
;               for (int j = 0; j < 4; ++j) {
;                 const int row = m0 + ai * 128 + wr8 * 64 + m * 16 + fq * 4 + j;
;                 float v = acc[ai][bj][m][n][j] * sc;
;                 if (gate) v = v * __builtin_amdgcn_rcpf(1.f + __expf(-v));
;                 dst[(size_t)row * dstr + fr] = f2bf(v);
;               }
	v_rcp_f32_e32 v143, v143
	v_rcp_f32_e32 v145, v145
	v_mul_f32_e32 v28, v28, v143
	v_mul_f32_e32 v29, v29, v145
	v_cvt_pk_bf16_f32 v138, v28, v29
	v_add_u32_e32 v139, 0x15c00, v134
	v_add_u32_e32 v140, 0x15c00, v135
	global_store_short v139, v138, s[8:9]
	global_store_short_d16_hi v140, v138, s[8:9]
	v_mul_f32_e32 v141, 0xbfb8aa3b, v22
	v_mul_f32_e32 v142, 0xbfb8aa3b, v23
	v_exp_f32_e32 v141, v141
	v_exp_f32_e32 v142, v142
	v_add_f32_e32 v141, 1.0, v141
	v_add_f32_e32 v142, 1.0, v142
	v_rcp_f32_e32 v141, v141
	v_rcp_f32_e32 v142, v142
	v_mul_f32_e32 v22, v22, v141
	v_mul_f32_e32 v23, v23, v142
	v_cvt_pk_bf16_f32 v137, v22, v23
	v_add_u32_e32 v139, 0x2b800, v132
	v_add_u32_e32 v140, 0x2b800, v133
	global_store_short v139, v137, s[8:9]
	global_store_short_d16_hi v140, v137, s[8:9]
	v_mul_f32_e32 v143, 0xbfb8aa3b, v24
	v_mul_f32_e32 v145, 0xbfb8aa3b, v25
	v_exp_f32_e32 v143, v143
	v_exp_f32_e32 v145, v145
	v_add_f32_e32 v143, 1.0, v143
	v_add_f32_e32 v145, 1.0, v145
	v_rcp_f32_e32 v143, v143
	v_rcp_f32_e32 v145, v145
	v_mul_f32_e32 v24, v24, v143
	v_mul_f32_e32 v25, v25, v145
	v_cvt_pk_bf16_f32 v138, v24, v25
	v_add_u32_e32 v139, 0x2b800, v134
	v_add_u32_e32 v140, 0x2b800, v135
	global_store_short v139, v138, s[8:9]
	global_store_short_d16_hi v140, v138, s[8:9]
	v_mul_f32_e32 v141, 0xbfb8aa3b, v18
	v_mul_f32_e32 v142, 0xbfb8aa3b, v19
	v_exp_f32_e32 v141, v141
	v_exp_f32_e32 v142, v142
	v_add_f32_e32 v141, 1.0, v141
	v_add_f32_e32 v142, 1.0, v142
	v_rcp_f32_e32 v141, v141
	v_rcp_f32_e32 v142, v142
	v_mul_f32_e32 v18, v18, v141
	v_mul_f32_e32 v19, v19, v142
	v_cvt_pk_bf16_f32 v137, v18, v19
	v_add_u32_e32 v139, 0x41400, v132
	v_add_u32_e32 v140, 0x41400, v133
	global_store_short v139, v137, s[8:9]
	global_store_short_d16_hi v140, v137, s[8:9]
	v_mul_f32_e32 v143, 0xbfb8aa3b, v20
	v_mul_f32_e32 v145, 0xbfb8aa3b, v21
	v_exp_f32_e32 v143, v143
	v_exp_f32_e32 v145, v145
	v_add_f32_e32 v143, 1.0, v143
	v_add_f32_e32 v145, 1.0, v145
	v_rcp_f32_e32 v143, v143
	v_rcp_f32_e32 v145, v145
	v_mul_f32_e32 v20, v20, v143
	v_mul_f32_e32 v21, v21, v145
	v_cvt_pk_bf16_f32 v138, v20, v21
	v_add_u32_e32 v139, 0x41400, v134
	v_add_u32_e32 v140, 0x41400, v135
	global_store_short v139, v138, s[8:9]
	global_store_short_d16_hi v140, v138, s[8:9]
	v_mul_f32_e32 v141, 0xbfb8aa3b, v14
	v_mul_f32_e32 v142, 0xbfb8aa3b, v15
	v_exp_f32_e32 v141, v141
	v_exp_f32_e32 v142, v142
	v_add_f32_e32 v141, 1.0, v141
	v_add_f32_e32 v142, 1.0, v142
	v_rcp_f32_e32 v141, v141
	v_rcp_f32_e32 v142, v142
	v_mul_f32_e32 v14, v14, v141
	v_mul_f32_e32 v15, v15, v142
	v_cvt_pk_bf16_f32 v137, v14, v15
	v_add_u32_e32 v139, 0xae000, v132
	v_add_u32_e32 v140, 0xae000, v133
	global_store_short v139, v137, s[8:9]
	global_store_short_d16_hi v140, v137, s[8:9]
	v_mul_f32_e32 v143, 0xbfb8aa3b, v16
	v_mul_f32_e32 v145, 0xbfb8aa3b, v17
	v_exp_f32_e32 v143, v143
	v_exp_f32_e32 v145, v145
	v_add_f32_e32 v143, 1.0, v143
	v_add_f32_e32 v145, 1.0, v145
	v_rcp_f32_e32 v143, v143
	v_rcp_f32_e32 v145, v145
	v_mul_f32_e32 v16, v16, v143
	v_mul_f32_e32 v17, v17, v145
	v_cvt_pk_bf16_f32 v138, v16, v17
	v_add_u32_e32 v139, 0xae000, v134
	v_add_u32_e32 v140, 0xae000, v135
	global_store_short v139, v138, s[8:9]
	global_store_short_d16_hi v140, v138, s[8:9]
	v_mul_f32_e32 v141, 0xbfb8aa3b, v10
	v_mul_f32_e32 v142, 0xbfb8aa3b, v11
	v_exp_f32_e32 v141, v141
	v_exp_f32_e32 v142, v142
	v_add_f32_e32 v141, 1.0, v141
	v_add_f32_e32 v142, 1.0, v142
	v_rcp_f32_e32 v141, v141
	v_rcp_f32_e32 v142, v142
	v_mul_f32_e32 v10, v10, v141
	v_mul_f32_e32 v11, v11, v142
	v_cvt_pk_bf16_f32 v137, v10, v11
	v_add_u32_e32 v139, 0xc3c00, v132
	v_add_u32_e32 v140, 0xc3c00, v133
	global_store_short v139, v137, s[8:9]
	global_store_short_d16_hi v140, v137, s[8:9]
	v_mul_f32_e32 v143, 0xbfb8aa3b, v12
	v_mul_f32_e32 v145, 0xbfb8aa3b, v13
	v_exp_f32_e32 v143, v143
	v_exp_f32_e32 v145, v145
	v_add_f32_e32 v143, 1.0, v143
	v_add_f32_e32 v145, 1.0, v145
	v_rcp_f32_e32 v143, v143
	v_rcp_f32_e32 v145, v145
	v_mul_f32_e32 v12, v12, v143
	v_mul_f32_e32 v13, v13, v145
	v_cvt_pk_bf16_f32 v138, v12, v13
	v_add_u32_e32 v139, 0xc3c00, v134
	v_add_u32_e32 v140, 0xc3c00, v135
	global_store_short v139, v138, s[8:9]
	global_store_short_d16_hi v140, v138, s[8:9]
	v_mul_f32_e32 v141, 0xbfb8aa3b, v6
	v_mul_f32_e32 v142, 0xbfb8aa3b, v7
	v_exp_f32_e32 v141, v141
	v_exp_f32_e32 v142, v142
	v_add_f32_e32 v141, 1.0, v141
	v_add_f32_e32 v142, 1.0, v142
	v_rcp_f32_e32 v141, v141
	v_rcp_f32_e32 v142, v142
	v_mul_f32_e32 v6, v6, v141
	v_mul_f32_e32 v7, v7, v142
	v_cvt_pk_bf16_f32 v137, v6, v7
	v_add_u32_e32 v139, 0xd9800, v132
	v_add_u32_e32 v140, 0xd9800, v133
	global_store_short v139, v137, s[8:9]
	global_store_short_d16_hi v140, v137, s[8:9]
	v_mul_f32_e32 v143, 0xbfb8aa3b, v8
	v_mul_f32_e32 v145, 0xbfb8aa3b, v9
	v_exp_f32_e32 v143, v143
	v_exp_f32_e32 v145, v145
	v_add_f32_e32 v143, 1.0, v143
	v_add_f32_e32 v145, 1.0, v145
	v_rcp_f32_e32 v143, v143
	v_rcp_f32_e32 v145, v145
	v_mul_f32_e32 v8, v8, v143
	v_mul_f32_e32 v9, v9, v145
	v_cvt_pk_bf16_f32 v138, v8, v9
	v_add_u32_e32 v139, 0xd9800, v134
	v_add_u32_e32 v140, 0xd9800, v135
	global_store_short v139, v138, s[8:9]
	global_store_short_d16_hi v140, v138, s[8:9]
	v_mul_f32_e32 v141, 0xbfb8aa3b, v0
	v_mul_f32_e32 v142, 0xbfb8aa3b, v1
	v_exp_f32_e32 v141, v141
	v_exp_f32_e32 v142, v142
	v_add_f32_e32 v141, 1.0, v141
	v_add_f32_e32 v142, 1.0, v142
	v_rcp_f32_e32 v141, v141
	v_rcp_f32_e32 v142, v142
	v_mul_f32_e32 v0, v0, v141
	v_mul_f32_e32 v1, v1, v142
	v_cvt_pk_bf16_f32 v137, v0, v1
	v_add_u32_e32 v139, 0xef400, v132
	v_add_u32_e32 v140, 0xef400, v133
	global_store_short v139, v137, s[8:9]
	global_store_short_d16_hi v140, v137, s[8:9]
	v_mul_f32_e32 v143, 0xbfb8aa3b, v2
	v_mul_f32_e32 v145, 0xbfb8aa3b, v3
	v_exp_f32_e32 v143, v143
	v_exp_f32_e32 v145, v145
	v_add_f32_e32 v143, 1.0, v143
	v_add_f32_e32 v145, 1.0, v145
	v_rcp_f32_e32 v143, v143
	v_rcp_f32_e32 v145, v145
	v_mul_f32_e32 v2, v2, v143
	v_mul_f32_e32 v3, v3, v145
	v_cvt_pk_bf16_f32 v138, v2, v3
	v_add_u32_e32 v139, 0xef400, v134
	v_add_u32_e32 v140, 0xef400, v135
	global_store_short v139, v138, s[8:9]
	global_store_short_d16_hi v140, v138, s[8:9]
	s_branch .Lipe3_done

; DI u16 f2bf(float x) { unsigned u = __float_as_uint(x); u += 0x7fffu + ((u >> 16) & 1u); return (u16)(u >> 16); }
; DI void phase_inproj(const Params& p, int layer, char* lds) {
;     ...
;           else if (cw >= C_SK && cw < C_SV) { const int o = cw - C_SK; dst = (u16*)(p.ws + OFF_SK) + ((size_t)(bb * 1 * S + (o >> 6) * S) << 6) + (o & 63); dstr = 64; }
;           else if (cw >= C_SV && cw < C_GATE) { const int o = cw - C_SV; dst = (u16*)(p.ws + OFF_SV) + ((size_t)(bb * 1 * S + (o >> 6) * S) << 6) + (o & 63); dstr = 64; }
;         }
;         if (cw < DIN) {
;           float sc = 1.f;
;           if (col >= C_DQ && col < C_DK) sc = SC_DQ;
;           if (col >= C_SQ && col < C_SK) sc = SC_SQ;
;           const bool gate = col >= C_GATE;
; #pragma unroll
;           for (int ai = 0; ai < 2; ++ai)
; #pragma unroll
;             for (int m = 0; m < 4; ++m) {
; #pragma unroll
;               for (int j = 0; j < 4; ++j) {
;                 const int row = m0 + ai * 128 + wr8 * 64 + m * 16 + fq * 4 + j;
;                 float v = acc[ai][bj][m][n][j] * sc;
;                 if (gate) v = v * __builtin_amdgcn_rcpf(1.f + __expf(-v));
;                 dst[(size_t)row * dstr + fr] = f2bf(v);
;               }
;               __builtin_amdgcn_sched_barrier(0);
;             }
;         }
.Lipe3_kv:
	v_cvt_pk_bf16_f32 v137, v30, v31
	global_store_short v136, v137, s[8:9] offset:0
	global_store_short_d16_hi v136, v137, s[8:9] offset:128
	v_cvt_pk_bf16_f32 v138, v32, v33
	global_store_short v136, v138, s[8:9] offset:256
	global_store_short_d16_hi v136, v138, s[8:9] offset:384
	v_add_u32_e32 v139, 0x800, v136
	v_cvt_pk_bf16_f32 v137, v26, v27
	global_store_short v139, v137, s[8:9] offset:0
	global_store_short_d16_hi v139, v137, s[8:9] offset:128
	v_cvt_pk_bf16_f32 v138, v28, v29
	global_store_short v139, v138, s[8:9] offset:256
	global_store_short_d16_hi v139, v138, s[8:9] offset:384
	v_add_u32_e32 v139, 0x1000, v136
	v_cvt_pk_bf16_f32 v137, v22, v23
	global_store_short v139, v137, s[8:9] offset:0
	global_store_short_d16_hi v139, v137, s[8:9] offset:128
	v_cvt_pk_bf16_f32 v138, v24, v25
	global_store_short v139, v138, s[8:9] offset:256
	global_store_short_d16_hi v139, v138, s[8:9] offset:384
	v_add_u32_e32 v139, 0x1800, v136
	v_cvt_pk_bf16_f32 v137, v18, v19
	global_store_short v139, v137, s[8:9] offset:0
	global_store_short_d16_hi v139, v137, s[8:9] offset:128
	v_cvt_pk_bf16_f32 v138, v20, v21
	global_store_short v139, v138, s[8:9] offset:256
	global_store_short_d16_hi v139, v138, s[8:9] offset:384
	v_add_u32_e32 v139, 0x4000, v136
	v_cvt_pk_bf16_f32 v137, v14, v15
	global_store_short v139, v137, s[8:9] offset:0
	global_store_short_d16_hi v139, v137, s[8:9] offset:128
	v_cvt_pk_bf16_f32 v138, v16, v17
	global_store_short v139, v138, s[8:9] offset:256
	global_store_short_d16_hi v139, v138, s[8:9] offset:384
	v_add_u32_e32 v139, 0x4800, v136
	v_cvt_pk_bf16_f32 v137, v10, v11
	global_store_short v139, v137, s[8:9] offset:0
	global_store_short_d16_hi v139, v137, s[8:9] offset:128
	v_cvt_pk_bf16_f32 v138, v12, v13
	global_store_short v139, v138, s[8:9] offset:256
	global_store_short_d16_hi v139, v138, s[8:9] offset:384
	v_add_u32_e32 v139, 0x5000, v136
	v_cvt_pk_bf16_f32 v137, v6, v7
	global_store_short v139, v137, s[8:9] offset:0
	global_store_short_d16_hi v139, v137, s[8:9] offset:128
	v_cvt_pk_bf16_f32 v138, v8, v9
	global_store_short v139, v138, s[8:9] offset:256
	global_store_short_d16_hi v139, v138, s[8:9] offset:384
	v_add_u32_e32 v139, 0x5800, v136
	v_cvt_pk_bf16_f32 v137, v0, v1
	global_store_short v139, v137, s[8:9] offset:0
	global_store_short_d16_hi v139, v137, s[8:9] offset:128
	v_cvt_pk_bf16_f32 v138, v2, v3
	global_store_short v139, v138, s[8:9] offset:256
	global_store_short_d16_hi v139, v138, s[8:9] offset:384
.Lipe3_done:
	s_mov_b64 s[4:5], -1
	s_branch .LBB0_81
